# post-K-loop MFMA->VALU pads trimmed from 32 to the required 8 wait states at the four live epilogue heads
# speedup vs baseline: 1.0037x; 1.0037x over previous
.LBB0_275:
	s_nop 7
	s_cmpk_lt_i32 s72, 0x5e
	s_mov_b64 s[74:75], -1
	s_cbranch_scc0 .LBB0_277
	v_lshl_add_u32 v152, s70, 8, v161
	v_lshl_or_b32 v146, s72, 8, v163
	v_ashrrev_i32_e32 v147, 31, v146
	v_ashrrev_i32_e32 v153, 31, v152
	v_pk_add_f32 v[156:157], v[124:125], 0 op_sel_hi:[1,0]
	v_lshl_add_u64 v[150:151], v[146:147], 1, s[18:19]
	v_lshlrev_b64 v[146:147], 11, v[152:153]
	v_lshl_add_u64 v[148:149], v[150:151], 0, v[146:147]
	v_fma_f32 v146, |v156|, s38, 1.0
	v_fma_f32 v147, |v157|, s38, 1.0
	v_pk_add_f32 v[154:155], v[126:127], 0 op_sel_hi:[1,0]
	v_rcp_f32_e32 v174, v146
	v_rcp_f32_e32 v175, v147
	v_mov_b64_e32 v[146:147], s[42:43]
	v_pk_mul_f32 v[180:181], v[156:157], v[156:157]
	v_pk_fma_f32 v[178:179], v[174:175], s[40:41], v[146:147] op_sel_hi:[1,0,0]
	v_pk_mul_f32 v[180:181], v[180:181], s[50:51] op_sel_hi:[1,0]
	v_pk_fma_f32 v[178:179], v[174:175], v[178:179], s[44:45] op_sel_hi:[1,1,0]
	v_exp_f32_e32 v180, v180
	v_exp_f32_e32 v181, v181
	v_fma_f32 v182, |v154|, s38, 1.0
	v_fma_f32 v183, |v155|, s38, 1.0
	v_pk_fma_f32 v[178:179], v[174:175], v[178:179], s[46:47] op_sel_hi:[1,1,0]
	v_rcp_f32_e32 v182, v182
	v_rcp_f32_e32 v183, v183
	v_pk_fma_f32 v[178:179], v[174:175], v[178:179], s[48:49] op_sel_hi:[1,1,0]
	v_max_f32_e32 v172, 0, v156
	v_pk_mul_f32 v[174:175], v[174:175], v[178:179]
	v_pk_mul_f32 v[178:179], v[154:155], v[154:155]
	v_max_f32_e32 v173, 0, v157
	v_pk_mul_f32 v[174:175], v[180:181], v[174:175]
	v_pk_add_f32 v[170:171], v[120:121], 0 op_sel_hi:[1,0]
	v_fma_f32 v156, -|v156|, v174, v172
	v_fma_f32 v157, -|v157|, v175, v173
	v_pk_fma_f32 v[172:173], v[182:183], s[40:41], v[146:147] op_sel_hi:[1,0,0]
	v_pk_mul_f32 v[174:175], v[178:179], s[50:51] op_sel_hi:[1,0]
	v_pk_fma_f32 v[172:173], v[182:183], v[172:173], s[44:45] op_sel_hi:[1,1,0]
	v_exp_f32_e32 v174, v174
	v_exp_f32_e32 v175, v175
	v_pk_fma_f32 v[172:173], v[182:183], v[172:173], s[46:47] op_sel_hi:[1,1,0]
	v_pk_add_f32 v[158:159], v[122:123], 0 op_sel_hi:[1,0]
	v_pk_fma_f32 v[172:173], v[182:183], v[172:173], s[48:49] op_sel_hi:[1,1,0]
	v_max_f32_e32 v176, 0, v154
	v_pk_mul_f32 v[172:173], v[182:183], v[172:173]
	v_max_f32_e32 v177, 0, v155
	v_pk_mul_f32 v[172:173], v[174:175], v[172:173]
	v_fma_f32 v178, |v170|, s38, 1.0
	v_fma_f32 v179, |v171|, s38, 1.0
	v_pk_mul_f32 v[180:181], v[170:171], v[170:171]
	v_rcp_f32_e32 v178, v178
	v_rcp_f32_e32 v179, v179
	v_fma_f32 v172, -|v154|, v172, v176
	v_fma_f32 v173, -|v155|, v173, v177
	v_pk_fma_f32 v[176:177], v[178:179], s[40:41], v[146:147] op_sel_hi:[1,0,0]
	v_pk_mul_f32 v[180:181], v[180:181], s[50:51] op_sel_hi:[1,0]
	v_pk_fma_f32 v[176:177], v[178:179], v[176:177], s[44:45] op_sel_hi:[1,1,0]
	v_exp_f32_e32 v180, v180
	v_exp_f32_e32 v181, v181
	v_fma_f32 v182, |v158|, s38, 1.0
	v_fma_f32 v183, |v159|, s38, 1.0
	v_pk_fma_f32 v[176:177], v[178:179], v[176:177], s[46:47] op_sel_hi:[1,1,0]
	v_rcp_f32_e32 v182, v182
	v_rcp_f32_e32 v183, v183
	v_pk_fma_f32 v[176:177], v[178:179], v[176:177], s[48:49] op_sel_hi:[1,1,0]
	v_max_f32_e32 v174, 0, v170
	v_pk_mul_f32 v[176:177], v[178:179], v[176:177]
	v_pk_mul_f32 v[178:179], v[158:159], v[158:159]
	v_max_f32_e32 v175, 0, v171
	v_pk_mul_f32 v[176:177], v[180:181], v[176:177]
	v_max_f32_e32 v154, 0, v158
	v_fma_f32 v170, -|v170|, v176, v174
	v_fma_f32 v171, -|v171|, v177, v175
	v_pk_fma_f32 v[174:175], v[182:183], s[40:41], v[146:147] op_sel_hi:[1,0,0]
	v_pk_mul_f32 v[176:177], v[178:179], s[50:51] op_sel_hi:[1,0]
	v_pk_fma_f32 v[174:175], v[182:183], v[174:175], s[44:45] op_sel_hi:[1,1,0]
	v_exp_f32_e32 v176, v176
	v_exp_f32_e32 v177, v177
	v_pk_fma_f32 v[174:175], v[182:183], v[174:175], s[46:47] op_sel_hi:[1,1,0]
	v_max_f32_e32 v155, 0, v159
	v_pk_fma_f32 v[174:175], v[182:183], v[174:175], s[48:49] op_sel_hi:[1,1,0]
	s_mov_b64 s[0:1], 0x40000
	v_pk_mul_f32 v[174:175], v[182:183], v[174:175]
	s_mov_b64 s[74:75], 0
	v_pk_mul_f32 v[174:175], v[176:177], v[174:175]
	s_nop 0
	v_fma_f32 v158, -|v158|, v174, v154
	v_fma_f32 v159, -|v159|, v175, v155
	v_cvt_pk_bf16_f32 v154, v156, v157
	v_cvt_pk_bf16_f32 v155, v172, v173
	v_cvt_pk_bf16_f32 v156, v170, v171
	v_pk_add_f32 v[174:175], v[112:113], 0 op_sel_hi:[1,0]
	v_cvt_pk_bf16_f32 v157, v158, v159
	global_store_dwordx4 v[148:149], v[154:157], off
	v_pk_add_f32 v[158:159], v[114:115], 0 op_sel_hi:[1,0]
	s_nop 0
	v_pk_add_f32 v[156:157], v[116:117], 0 op_sel_hi:[1,0]
	v_pk_add_f32 v[154:155], v[118:119], 0 op_sel_hi:[1,0]
	v_fma_f32 v172, |v156|, s38, 1.0
	v_fma_f32 v173, |v157|, s38, 1.0
	v_pk_mul_f32 v[180:181], v[156:157], v[156:157]
	v_rcp_f32_e32 v172, v172
	v_rcp_f32_e32 v173, v173
	v_pk_mul_f32 v[180:181], v[180:181], s[50:51] op_sel_hi:[1,0]
	v_pk_fma_f32 v[178:179], v[172:173], s[40:41], v[146:147] op_sel_hi:[1,0,0]
	v_exp_f32_e32 v180, v180
	v_pk_fma_f32 v[178:179], v[172:173], v[178:179], s[44:45] op_sel_hi:[1,1,0]
	v_exp_f32_e32 v181, v181
	v_fma_f32 v182, |v154|, s38, 1.0
	v_fma_f32 v183, |v155|, s38, 1.0
	v_pk_fma_f32 v[178:179], v[172:173], v[178:179], s[46:47] op_sel_hi:[1,1,0]
	v_rcp_f32_e32 v182, v182
	v_rcp_f32_e32 v183, v183
	v_pk_fma_f32 v[178:179], v[172:173], v[178:179], s[48:49] op_sel_hi:[1,1,0]
	v_max_f32_e32 v170, 0, v156
	v_pk_mul_f32 v[172:173], v[172:173], v[178:179]
	v_pk_mul_f32 v[178:179], v[154:155], v[154:155]
	v_max_f32_e32 v171, 0, v157
	v_pk_mul_f32 v[172:173], v[180:181], v[172:173]
	v_max_f32_e32 v176, 0, v154
	v_fma_f32 v156, -|v156|, v172, v170
	v_fma_f32 v157, -|v157|, v173, v171
	v_pk_fma_f32 v[170:171], v[182:183], s[40:41], v[146:147] op_sel_hi:[1,0,0]
	v_pk_mul_f32 v[172:173], v[178:179], s[50:51] op_sel_hi:[1,0]
	v_pk_fma_f32 v[170:171], v[182:183], v[170:171], s[44:45] op_sel_hi:[1,1,0]
	v_exp_f32_e32 v172, v172
	v_exp_f32_e32 v173, v173
	v_pk_fma_f32 v[170:171], v[182:183], v[170:171], s[46:47] op_sel_hi:[1,1,0]
	v_max_f32_e32 v177, 0, v155
	v_pk_fma_f32 v[170:171], v[182:183], v[170:171], s[48:49] op_sel_hi:[1,1,0]
	v_pk_mul_f32 v[180:181], v[174:175], v[174:175]
	v_pk_mul_f32 v[170:171], v[182:183], v[170:171]
	v_pk_mul_f32 v[180:181], v[180:181], s[50:51] op_sel_hi:[1,0]
	v_pk_mul_f32 v[170:171], v[172:173], v[170:171]
	v_fma_f32 v178, |v174|, s38, 1.0
	v_fma_f32 v179, |v175|, s38, 1.0
	v_fma_f32 v170, -|v154|, v170, v176
	v_fma_f32 v171, -|v155|, v171, v177
	v_rcp_f32_e32 v178, v178
	v_rcp_f32_e32 v179, v179
	v_exp_f32_e32 v180, v180
	v_pk_fma_f32 v[176:177], v[178:179], s[40:41], v[146:147] op_sel_hi:[1,0,0]
	v_exp_f32_e32 v181, v181
	v_pk_fma_f32 v[176:177], v[178:179], v[176:177], s[44:45] op_sel_hi:[1,1,0]
	v_fma_f32 v182, |v158|, s38, 1.0
	v_fma_f32 v183, |v159|, s38, 1.0
	v_pk_fma_f32 v[176:177], v[178:179], v[176:177], s[46:47] op_sel_hi:[1,1,0]
	v_rcp_f32_e32 v182, v182
	v_rcp_f32_e32 v183, v183
	v_pk_fma_f32 v[176:177], v[178:179], v[176:177], s[48:49] op_sel_hi:[1,1,0]
	v_max_f32_e32 v172, 0, v174
	v_pk_mul_f32 v[176:177], v[178:179], v[176:177]
	v_pk_mul_f32 v[178:179], v[158:159], v[158:159]
	v_max_f32_e32 v173, 0, v175
	v_pk_mul_f32 v[176:177], v[180:181], v[176:177]
	v_max_f32_e32 v154, 0, v158
	v_fma_f32 v172, -|v174|, v176, v172
	v_fma_f32 v173, -|v175|, v177, v173
	v_pk_fma_f32 v[174:175], v[182:183], s[40:41], v[146:147] op_sel_hi:[1,0,0]
	v_pk_mul_f32 v[176:177], v[178:179], s[50:51] op_sel_hi:[1,0]
	v_pk_fma_f32 v[174:175], v[182:183], v[174:175], s[44:45] op_sel_hi:[1,1,0]
	v_exp_f32_e32 v176, v176
	v_exp_f32_e32 v177, v177
	v_pk_fma_f32 v[174:175], v[182:183], v[174:175], s[46:47] op_sel_hi:[1,1,0]
	v_max_f32_e32 v155, 0, v159
	v_pk_fma_f32 v[174:175], v[182:183], v[174:175], s[48:49] op_sel_hi:[1,1,0]
	s_nop 0
	v_pk_mul_f32 v[174:175], v[182:183], v[174:175]
	s_nop 0
	v_pk_mul_f32 v[174:175], v[176:177], v[174:175]
	v_pk_add_f32 v[176:177], v[104:105], 0 op_sel_hi:[1,0]
	v_fma_f32 v158, -|v158|, v174, v154
	v_fma_f32 v159, -|v159|, v175, v155
	v_cvt_pk_bf16_f32 v154, v156, v157
	v_cvt_pk_bf16_f32 v155, v170, v171
	v_cvt_pk_bf16_f32 v156, v172, v173
	v_pk_add_f32 v[170:171], v[106:107], 0 op_sel_hi:[1,0]
	v_cvt_pk_bf16_f32 v157, v158, v159
	v_pk_add_f32 v[158:159], v[108:109], 0 op_sel_hi:[1,0]
	global_store_dwordx4 v[148:149], v[154:157], off offset:256
	v_fma_f32 v174, |v158|, s38, 1.0
	v_fma_f32 v175, |v159|, s38, 1.0
	v_pk_add_f32 v[156:157], v[110:111], 0 op_sel_hi:[1,0]
	v_rcp_f32_e32 v174, v174
	v_rcp_f32_e32 v175, v175
	v_pk_mul_f32 v[182:183], v[158:159], v[158:159]
	v_pk_fma_f32 v[180:181], v[174:175], s[40:41], v[146:147] op_sel_hi:[1,0,0]
	v_pk_mul_f32 v[182:183], v[182:183], s[50:51] op_sel_hi:[1,0]
	v_pk_fma_f32 v[180:181], v[174:175], v[180:181], s[44:45] op_sel_hi:[1,1,0]
	v_exp_f32_e32 v182, v182
	v_exp_f32_e32 v183, v183
	v_fma_f32 v184, |v156|, s38, 1.0
	v_fma_f32 v185, |v157|, s38, 1.0
	v_pk_fma_f32 v[180:181], v[174:175], v[180:181], s[46:47] op_sel_hi:[1,1,0]
	v_rcp_f32_e32 v184, v184
	v_rcp_f32_e32 v185, v185
	v_pk_fma_f32 v[180:181], v[174:175], v[180:181], s[48:49] op_sel_hi:[1,1,0]
	v_max_f32_e32 v172, 0, v158
	v_pk_mul_f32 v[174:175], v[174:175], v[180:181]
	v_pk_mul_f32 v[180:181], v[156:157], v[156:157]
	v_max_f32_e32 v173, 0, v159
	v_pk_mul_f32 v[174:175], v[182:183], v[174:175]
	v_max_f32_e32 v178, 0, v156
	v_fma_f32 v158, -|v158|, v174, v172
	v_fma_f32 v159, -|v159|, v175, v173
	v_pk_fma_f32 v[172:173], v[184:185], s[40:41], v[146:147] op_sel_hi:[1,0,0]
	v_pk_mul_f32 v[174:175], v[180:181], s[50:51] op_sel_hi:[1,0]
	v_pk_fma_f32 v[172:173], v[184:185], v[172:173], s[44:45] op_sel_hi:[1,1,0]
	v_exp_f32_e32 v174, v174
	v_exp_f32_e32 v175, v175
	v_pk_fma_f32 v[172:173], v[184:185], v[172:173], s[46:47] op_sel_hi:[1,1,0]
	v_max_f32_e32 v179, 0, v157
	v_pk_fma_f32 v[172:173], v[184:185], v[172:173], s[48:49] op_sel_hi:[1,1,0]
	v_pk_mul_f32 v[182:183], v[176:177], v[176:177]
	v_pk_mul_f32 v[172:173], v[184:185], v[172:173]
	v_pk_mul_f32 v[182:183], v[182:183], s[50:51] op_sel_hi:[1,0]
	v_pk_mul_f32 v[172:173], v[174:175], v[172:173]
	v_fma_f32 v180, |v176|, s38, 1.0
	v_fma_f32 v181, |v177|, s38, 1.0
	v_fma_f32 v172, -|v156|, v172, v178
	v_fma_f32 v173, -|v157|, v173, v179
	v_rcp_f32_e32 v180, v180
	v_rcp_f32_e32 v181, v181
	v_exp_f32_e32 v182, v182
	v_pk_fma_f32 v[178:179], v[180:181], s[40:41], v[146:147] op_sel_hi:[1,0,0]
	v_exp_f32_e32 v183, v183
	v_pk_fma_f32 v[178:179], v[180:181], v[178:179], s[44:45] op_sel_hi:[1,1,0]
	v_fma_f32 v184, |v170|, s38, 1.0
	v_fma_f32 v185, |v171|, s38, 1.0
	v_pk_fma_f32 v[178:179], v[180:181], v[178:179], s[46:47] op_sel_hi:[1,1,0]
	v_rcp_f32_e32 v184, v184
	v_rcp_f32_e32 v185, v185
	v_pk_fma_f32 v[178:179], v[180:181], v[178:179], s[48:49] op_sel_hi:[1,1,0]
	v_max_f32_e32 v174, 0, v176
	v_pk_mul_f32 v[178:179], v[180:181], v[178:179]
	v_pk_mul_f32 v[180:181], v[170:171], v[170:171]
	v_max_f32_e32 v175, 0, v177
	v_pk_mul_f32 v[178:179], v[182:183], v[178:179]
	v_or_b32_e32 v154, 16, v152
	v_fma_f32 v174, -|v176|, v178, v174
	v_fma_f32 v175, -|v177|, v179, v175
	v_pk_fma_f32 v[176:177], v[184:185], s[40:41], v[146:147] op_sel_hi:[1,0,0]
	v_pk_mul_f32 v[178:179], v[180:181], s[50:51] op_sel_hi:[1,0]
	v_pk_fma_f32 v[176:177], v[184:185], v[176:177], s[44:45] op_sel_hi:[1,1,0]
	v_exp_f32_e32 v178, v178
	v_exp_f32_e32 v179, v179
	v_pk_fma_f32 v[176:177], v[184:185], v[176:177], s[46:47] op_sel_hi:[1,1,0]
	v_ashrrev_i32_e32 v155, 31, v154
	v_pk_fma_f32 v[176:177], v[184:185], v[176:177], s[48:49] op_sel_hi:[1,1,0]
	v_lshlrev_b64 v[154:155], 11, v[154:155]
	v_pk_mul_f32 v[176:177], v[184:185], v[176:177]
	v_max_f32_e32 v156, 0, v170
	v_max_f32_e32 v157, 0, v171
	v_pk_mul_f32 v[176:177], v[178:179], v[176:177]
	v_lshl_add_u64 v[154:155], v[150:151], 0, v[154:155]
	v_fma_f32 v170, -|v170|, v176, v156
	v_fma_f32 v171, -|v171|, v177, v157
	v_cvt_pk_bf16_f32 v156, v158, v159
	v_cvt_pk_bf16_f32 v157, v172, v173
	v_cvt_pk_bf16_f32 v158, v174, v175
	v_pk_add_f32 v[176:177], v[96:97], 0 op_sel_hi:[1,0]
	v_cvt_pk_bf16_f32 v159, v170, v171
	global_store_dwordx4 v[154:155], v[156:159], off
	v_pk_add_f32 v[170:171], v[98:99], 0 op_sel_hi:[1,0]
	s_nop 0
	v_pk_add_f32 v[158:159], v[100:101], 0 op_sel_hi:[1,0]
	v_pk_add_f32 v[156:157], v[102:103], 0 op_sel_hi:[1,0]
	v_fma_f32 v174, |v158|, s38, 1.0
	v_fma_f32 v175, |v159|, s38, 1.0
	v_pk_mul_f32 v[182:183], v[158:159], v[158:159]
	v_rcp_f32_e32 v174, v174
	v_rcp_f32_e32 v175, v175
	v_pk_mul_f32 v[182:183], v[182:183], s[50:51] op_sel_hi:[1,0]
	v_pk_fma_f32 v[180:181], v[174:175], s[40:41], v[146:147] op_sel_hi:[1,0,0]
	v_exp_f32_e32 v182, v182
	v_pk_fma_f32 v[180:181], v[174:175], v[180:181], s[44:45] op_sel_hi:[1,1,0]
	v_exp_f32_e32 v183, v183
	v_fma_f32 v184, |v156|, s38, 1.0
	v_fma_f32 v185, |v157|, s38, 1.0
	v_pk_fma_f32 v[180:181], v[174:175], v[180:181], s[46:47] op_sel_hi:[1,1,0]
	v_rcp_f32_e32 v184, v184
	v_rcp_f32_e32 v185, v185
	v_pk_fma_f32 v[180:181], v[174:175], v[180:181], s[48:49] op_sel_hi:[1,1,0]
	v_max_f32_e32 v172, 0, v158
	v_pk_mul_f32 v[174:175], v[174:175], v[180:181]
	v_pk_mul_f32 v[180:181], v[156:157], v[156:157]
	v_max_f32_e32 v173, 0, v159
	v_pk_mul_f32 v[174:175], v[182:183], v[174:175]
	v_max_f32_e32 v178, 0, v156
	v_fma_f32 v158, -|v158|, v174, v172
	v_fma_f32 v159, -|v159|, v175, v173
	v_pk_fma_f32 v[172:173], v[184:185], s[40:41], v[146:147] op_sel_hi:[1,0,0]
	v_pk_mul_f32 v[174:175], v[180:181], s[50:51] op_sel_hi:[1,0]
	v_pk_fma_f32 v[172:173], v[184:185], v[172:173], s[44:45] op_sel_hi:[1,1,0]
	v_exp_f32_e32 v174, v174
	v_exp_f32_e32 v175, v175
	v_pk_fma_f32 v[172:173], v[184:185], v[172:173], s[46:47] op_sel_hi:[1,1,0]
	v_max_f32_e32 v179, 0, v157
	v_pk_fma_f32 v[172:173], v[184:185], v[172:173], s[48:49] op_sel_hi:[1,1,0]
	v_pk_mul_f32 v[182:183], v[176:177], v[176:177]
	v_pk_mul_f32 v[172:173], v[184:185], v[172:173]
	v_pk_mul_f32 v[182:183], v[182:183], s[50:51] op_sel_hi:[1,0]
	v_pk_mul_f32 v[172:173], v[174:175], v[172:173]
	v_fma_f32 v180, |v176|, s38, 1.0
	v_fma_f32 v181, |v177|, s38, 1.0
	v_fma_f32 v172, -|v156|, v172, v178
	v_fma_f32 v173, -|v157|, v173, v179
	v_rcp_f32_e32 v180, v180
	v_rcp_f32_e32 v181, v181
	v_exp_f32_e32 v182, v182
	v_pk_fma_f32 v[178:179], v[180:181], s[40:41], v[146:147] op_sel_hi:[1,0,0]
	v_exp_f32_e32 v183, v183
	v_pk_fma_f32 v[178:179], v[180:181], v[178:179], s[44:45] op_sel_hi:[1,1,0]
	v_fma_f32 v184, |v170|, s38, 1.0
	v_fma_f32 v185, |v171|, s38, 1.0
	v_pk_fma_f32 v[178:179], v[180:181], v[178:179], s[46:47] op_sel_hi:[1,1,0]
	v_rcp_f32_e32 v184, v184
	v_rcp_f32_e32 v185, v185
	v_pk_fma_f32 v[178:179], v[180:181], v[178:179], s[48:49] op_sel_hi:[1,1,0]
	v_max_f32_e32 v174, 0, v176
	v_pk_mul_f32 v[178:179], v[180:181], v[178:179]
	v_pk_mul_f32 v[180:181], v[170:171], v[170:171]
	v_max_f32_e32 v175, 0, v177
	v_pk_mul_f32 v[178:179], v[182:183], v[178:179]
	v_max_f32_e32 v156, 0, v170
	v_fma_f32 v174, -|v176|, v178, v174
	v_fma_f32 v175, -|v177|, v179, v175
	v_pk_fma_f32 v[176:177], v[184:185], s[40:41], v[146:147] op_sel_hi:[1,0,0]
	v_pk_mul_f32 v[178:179], v[180:181], s[50:51] op_sel_hi:[1,0]
	v_pk_fma_f32 v[176:177], v[184:185], v[176:177], s[44:45] op_sel_hi:[1,1,0]
	v_exp_f32_e32 v178, v178
	v_exp_f32_e32 v179, v179
	v_pk_fma_f32 v[176:177], v[184:185], v[176:177], s[46:47] op_sel_hi:[1,1,0]
	v_max_f32_e32 v157, 0, v171
	v_pk_fma_f32 v[176:177], v[184:185], v[176:177], s[48:49] op_sel_hi:[1,1,0]
	s_nop 0
	v_pk_mul_f32 v[176:177], v[184:185], v[176:177]
	s_nop 0
	v_pk_mul_f32 v[176:177], v[178:179], v[176:177]
	s_nop 0
	v_fma_f32 v170, -|v170|, v176, v156
	v_fma_f32 v171, -|v171|, v177, v157
	v_cvt_pk_bf16_f32 v156, v158, v159
	v_cvt_pk_bf16_f32 v157, v172, v173
	v_cvt_pk_bf16_f32 v158, v174, v175
	v_pk_add_f32 v[176:177], v[88:89], 0 op_sel_hi:[1,0]
	v_cvt_pk_bf16_f32 v159, v170, v171
	global_store_dwordx4 v[154:155], v[156:159], off offset:256
	v_pk_add_f32 v[170:171], v[90:91], 0 op_sel_hi:[1,0]
	v_or_b32_e32 v154, 32, v152
	v_pk_add_f32 v[158:159], v[92:93], 0 op_sel_hi:[1,0]
	v_pk_add_f32 v[156:157], v[94:95], 0 op_sel_hi:[1,0]
	v_fma_f32 v174, |v158|, s38, 1.0
	v_fma_f32 v175, |v159|, s38, 1.0
	v_pk_mul_f32 v[182:183], v[158:159], v[158:159]
	v_rcp_f32_e32 v174, v174
	v_rcp_f32_e32 v175, v175
	v_pk_mul_f32 v[182:183], v[182:183], s[50:51] op_sel_hi:[1,0]
	v_pk_fma_f32 v[180:181], v[174:175], s[40:41], v[146:147] op_sel_hi:[1,0,0]
	v_exp_f32_e32 v182, v182
	v_pk_fma_f32 v[180:181], v[174:175], v[180:181], s[44:45] op_sel_hi:[1,1,0]
	v_exp_f32_e32 v183, v183
	v_fma_f32 v184, |v156|, s38, 1.0
	v_fma_f32 v185, |v157|, s38, 1.0
	v_pk_fma_f32 v[180:181], v[174:175], v[180:181], s[46:47] op_sel_hi:[1,1,0]
	v_rcp_f32_e32 v184, v184
	v_rcp_f32_e32 v185, v185
	v_pk_fma_f32 v[180:181], v[174:175], v[180:181], s[48:49] op_sel_hi:[1,1,0]
	v_max_f32_e32 v172, 0, v158
	v_pk_mul_f32 v[174:175], v[174:175], v[180:181]
	v_pk_mul_f32 v[180:181], v[156:157], v[156:157]
	v_max_f32_e32 v173, 0, v159
	v_pk_mul_f32 v[174:175], v[182:183], v[174:175]
	v_max_f32_e32 v178, 0, v156
	v_fma_f32 v158, -|v158|, v174, v172
	v_fma_f32 v159, -|v159|, v175, v173
	v_pk_fma_f32 v[172:173], v[184:185], s[40:41], v[146:147] op_sel_hi:[1,0,0]
	v_pk_mul_f32 v[174:175], v[180:181], s[50:51] op_sel_hi:[1,0]
	v_pk_fma_f32 v[172:173], v[184:185], v[172:173], s[44:45] op_sel_hi:[1,1,0]
	v_exp_f32_e32 v174, v174
	v_exp_f32_e32 v175, v175
	v_pk_fma_f32 v[172:173], v[184:185], v[172:173], s[46:47] op_sel_hi:[1,1,0]
	v_max_f32_e32 v179, 0, v157
	v_pk_fma_f32 v[172:173], v[184:185], v[172:173], s[48:49] op_sel_hi:[1,1,0]
	v_pk_mul_f32 v[182:183], v[176:177], v[176:177]
	v_pk_mul_f32 v[172:173], v[184:185], v[172:173]
	v_pk_mul_f32 v[182:183], v[182:183], s[50:51] op_sel_hi:[1,0]
	v_pk_mul_f32 v[172:173], v[174:175], v[172:173]
	v_fma_f32 v180, |v176|, s38, 1.0
	v_fma_f32 v181, |v177|, s38, 1.0
	v_fma_f32 v172, -|v156|, v172, v178
	v_fma_f32 v173, -|v157|, v173, v179
	v_rcp_f32_e32 v180, v180
	v_rcp_f32_e32 v181, v181
	v_exp_f32_e32 v182, v182
	v_pk_fma_f32 v[178:179], v[180:181], s[40:41], v[146:147] op_sel_hi:[1,0,0]
	v_exp_f32_e32 v183, v183
	v_pk_fma_f32 v[178:179], v[180:181], v[178:179], s[44:45] op_sel_hi:[1,1,0]
	v_fma_f32 v184, |v170|, s38, 1.0
	v_fma_f32 v185, |v171|, s38, 1.0
	v_pk_fma_f32 v[178:179], v[180:181], v[178:179], s[46:47] op_sel_hi:[1,1,0]
	v_rcp_f32_e32 v184, v184
	v_rcp_f32_e32 v185, v185
	v_pk_fma_f32 v[178:179], v[180:181], v[178:179], s[48:49] op_sel_hi:[1,1,0]
	v_max_f32_e32 v174, 0, v176
	v_pk_mul_f32 v[178:179], v[180:181], v[178:179]
	v_pk_mul_f32 v[180:181], v[170:171], v[170:171]
	v_max_f32_e32 v175, 0, v177
	v_pk_mul_f32 v[178:179], v[182:183], v[178:179]
	v_ashrrev_i32_e32 v155, 31, v154
	v_fma_f32 v174, -|v176|, v178, v174
	v_fma_f32 v175, -|v177|, v179, v175
	v_pk_fma_f32 v[176:177], v[184:185], s[40:41], v[146:147] op_sel_hi:[1,0,0]
	v_pk_mul_f32 v[178:179], v[180:181], s[50:51] op_sel_hi:[1,0]
	v_pk_fma_f32 v[176:177], v[184:185], v[176:177], s[44:45] op_sel_hi:[1,1,0]
	v_exp_f32_e32 v178, v178
	v_exp_f32_e32 v179, v179
	v_pk_fma_f32 v[176:177], v[184:185], v[176:177], s[46:47] op_sel_hi:[1,1,0]
	v_lshlrev_b64 v[154:155], 11, v[154:155]
	v_pk_fma_f32 v[176:177], v[184:185], v[176:177], s[48:49] op_sel_hi:[1,1,0]
	v_max_f32_e32 v156, 0, v170
	v_pk_mul_f32 v[176:177], v[184:185], v[176:177]
	v_max_f32_e32 v157, 0, v171
	v_pk_mul_f32 v[176:177], v[178:179], v[176:177]
	v_lshl_add_u64 v[154:155], v[150:151], 0, v[154:155]
	v_fma_f32 v170, -|v170|, v176, v156
	v_fma_f32 v171, -|v171|, v177, v157
	v_cvt_pk_bf16_f32 v156, v158, v159
	v_cvt_pk_bf16_f32 v157, v172, v173
	v_cvt_pk_bf16_f32 v158, v174, v175
	v_pk_add_f32 v[176:177], v[80:81], 0 op_sel_hi:[1,0]
	v_cvt_pk_bf16_f32 v159, v170, v171
	global_store_dwordx4 v[154:155], v[156:159], off
	v_pk_add_f32 v[170:171], v[82:83], 0 op_sel_hi:[1,0]
	v_or_b32_e32 v152, 48, v152
	v_pk_add_f32 v[158:159], v[84:85], 0 op_sel_hi:[1,0]
	v_pk_add_f32 v[156:157], v[86:87], 0 op_sel_hi:[1,0]
	v_fma_f32 v174, |v158|, s38, 1.0
	v_fma_f32 v175, |v159|, s38, 1.0
	v_pk_mul_f32 v[182:183], v[158:159], v[158:159]
	v_rcp_f32_e32 v174, v174
	v_rcp_f32_e32 v175, v175
	v_pk_mul_f32 v[182:183], v[182:183], s[50:51] op_sel_hi:[1,0]
	v_pk_fma_f32 v[180:181], v[174:175], s[40:41], v[146:147] op_sel_hi:[1,0,0]
	v_exp_f32_e32 v182, v182
	v_pk_fma_f32 v[180:181], v[174:175], v[180:181], s[44:45] op_sel_hi:[1,1,0]
	v_exp_f32_e32 v183, v183
	v_fma_f32 v184, |v156|, s38, 1.0
	v_fma_f32 v185, |v157|, s38, 1.0
	v_pk_fma_f32 v[180:181], v[174:175], v[180:181], s[46:47] op_sel_hi:[1,1,0]
	v_rcp_f32_e32 v184, v184
	v_rcp_f32_e32 v185, v185
	v_pk_fma_f32 v[180:181], v[174:175], v[180:181], s[48:49] op_sel_hi:[1,1,0]
	v_max_f32_e32 v172, 0, v158
	v_pk_mul_f32 v[174:175], v[174:175], v[180:181]
	v_pk_mul_f32 v[180:181], v[156:157], v[156:157]
	v_max_f32_e32 v173, 0, v159
	v_pk_mul_f32 v[174:175], v[182:183], v[174:175]
	v_max_f32_e32 v178, 0, v156
	v_fma_f32 v158, -|v158|, v174, v172
	v_fma_f32 v159, -|v159|, v175, v173
	v_pk_fma_f32 v[172:173], v[184:185], s[40:41], v[146:147] op_sel_hi:[1,0,0]
	v_pk_mul_f32 v[174:175], v[180:181], s[50:51] op_sel_hi:[1,0]
	v_pk_fma_f32 v[172:173], v[184:185], v[172:173], s[44:45] op_sel_hi:[1,1,0]
	v_exp_f32_e32 v174, v174
	v_exp_f32_e32 v175, v175
	v_pk_fma_f32 v[172:173], v[184:185], v[172:173], s[46:47] op_sel_hi:[1,1,0]
	v_max_f32_e32 v179, 0, v157
	v_pk_fma_f32 v[172:173], v[184:185], v[172:173], s[48:49] op_sel_hi:[1,1,0]
	v_pk_mul_f32 v[182:183], v[176:177], v[176:177]
	v_pk_mul_f32 v[172:173], v[184:185], v[172:173]
	v_pk_mul_f32 v[182:183], v[182:183], s[50:51] op_sel_hi:[1,0]
	v_pk_mul_f32 v[172:173], v[174:175], v[172:173]
	v_fma_f32 v180, |v176|, s38, 1.0
	v_fma_f32 v181, |v177|, s38, 1.0
	v_fma_f32 v172, -|v156|, v172, v178
	v_fma_f32 v173, -|v157|, v173, v179
	v_rcp_f32_e32 v180, v180
	v_rcp_f32_e32 v181, v181
	v_exp_f32_e32 v182, v182
	v_pk_fma_f32 v[178:179], v[180:181], s[40:41], v[146:147] op_sel_hi:[1,0,0]
	v_exp_f32_e32 v183, v183
	v_pk_fma_f32 v[178:179], v[180:181], v[178:179], s[44:45] op_sel_hi:[1,1,0]
	v_fma_f32 v184, |v170|, s38, 1.0
	v_fma_f32 v185, |v171|, s38, 1.0
	v_pk_fma_f32 v[178:179], v[180:181], v[178:179], s[46:47] op_sel_hi:[1,1,0]
	v_rcp_f32_e32 v184, v184
	v_rcp_f32_e32 v185, v185
	v_pk_fma_f32 v[178:179], v[180:181], v[178:179], s[48:49] op_sel_hi:[1,1,0]
	v_max_f32_e32 v174, 0, v176
	v_pk_mul_f32 v[178:179], v[180:181], v[178:179]
	v_pk_mul_f32 v[180:181], v[170:171], v[170:171]
	v_max_f32_e32 v175, 0, v177
	v_pk_mul_f32 v[178:179], v[182:183], v[178:179]
	v_max_f32_e32 v156, 0, v170
	v_fma_f32 v174, -|v176|, v178, v174
	v_fma_f32 v175, -|v177|, v179, v175
	v_pk_fma_f32 v[176:177], v[184:185], s[40:41], v[146:147] op_sel_hi:[1,0,0]
	v_pk_mul_f32 v[178:179], v[180:181], s[50:51] op_sel_hi:[1,0]
	v_pk_fma_f32 v[176:177], v[184:185], v[176:177], s[44:45] op_sel_hi:[1,1,0]
	v_exp_f32_e32 v178, v178
	v_exp_f32_e32 v179, v179
	v_pk_fma_f32 v[176:177], v[184:185], v[176:177], s[46:47] op_sel_hi:[1,1,0]
	v_max_f32_e32 v157, 0, v171
	v_pk_fma_f32 v[176:177], v[184:185], v[176:177], s[48:49] op_sel_hi:[1,1,0]
	v_ashrrev_i32_e32 v153, 31, v152
	v_pk_mul_f32 v[176:177], v[184:185], v[176:177]
	v_lshlrev_b64 v[152:153], 11, v[152:153]
	v_pk_mul_f32 v[176:177], v[178:179], v[176:177]
	v_lshl_add_u64 v[150:151], v[150:151], 0, v[152:153]
	v_fma_f32 v170, -|v170|, v176, v156
	v_fma_f32 v171, -|v171|, v177, v157
	v_cvt_pk_bf16_f32 v156, v158, v159
	v_cvt_pk_bf16_f32 v157, v172, v173
	v_cvt_pk_bf16_f32 v158, v174, v175
	v_pk_add_f32 v[152:153], v[78:79], 0 op_sel_hi:[1,0]
	v_cvt_pk_bf16_f32 v159, v170, v171
	global_store_dwordx4 v[154:155], v[156:159], off offset:256
	v_pk_add_f32 v[154:155], v[76:77], 0 op_sel_hi:[1,0]
	v_and_b32_e32 v175, 0x7fffffff, v153
	v_fma_f32 v170, |v154|, s38, 1.0
	v_fma_f32 v171, |v155|, s38, 1.0
	v_pk_mul_f32 v[178:179], v[154:155], v[154:155]
	v_rcp_f32_e32 v170, v170
	v_rcp_f32_e32 v171, v171
	v_and_b32_e32 v174, 0x7fffffff, v152
	v_pk_mul_f32 v[178:179], v[178:179], s[50:51] op_sel_hi:[1,0]
	v_pk_fma_f32 v[180:181], v[174:175], s[38:39], 1.0 op_sel_hi:[1,0,0]
	v_pk_fma_f32 v[176:177], v[170:171], s[40:41], v[146:147] op_sel_hi:[1,0,0]
	v_exp_f32_e32 v178, v178
	v_pk_fma_f32 v[176:177], v[170:171], v[176:177], s[44:45] op_sel_hi:[1,1,0]
	v_exp_f32_e32 v179, v179
	v_pk_fma_f32 v[176:177], v[170:171], v[176:177], s[46:47] op_sel_hi:[1,1,0]
	v_rcp_f32_e32 v180, v180
	v_rcp_f32_e32 v181, v181
	v_pk_fma_f32 v[176:177], v[170:171], v[176:177], s[48:49] op_sel_hi:[1,1,0]
	v_max_f32_e32 v158, 0, v154
	v_pk_mul_f32 v[170:171], v[170:171], v[176:177]
	v_pk_mul_f32 v[176:177], v[152:153], v[152:153]
	v_max_f32_e32 v159, 0, v155
	v_pk_mul_f32 v[170:171], v[178:179], v[170:171]
	v_pk_add_f32 v[172:173], v[72:73], 0 op_sel_hi:[1,0]
	v_fma_f32 v154, -|v154|, v170, v158
	v_fma_f32 v155, -|v155|, v171, v159
	v_pk_fma_f32 v[158:159], v[180:181], s[40:41], v[146:147] op_sel_hi:[1,0,0]
	v_pk_mul_f32 v[170:171], v[176:177], s[50:51] op_sel_hi:[1,0]
	v_pk_fma_f32 v[158:159], v[180:181], v[158:159], s[44:45] op_sel_hi:[1,1,0]
	v_exp_f32_e32 v170, v170
	v_exp_f32_e32 v171, v171
	v_pk_fma_f32 v[158:159], v[180:181], v[158:159], s[46:47] op_sel_hi:[1,1,0]
	v_pk_add_f32 v[156:157], v[74:75], 0 op_sel_hi:[1,0]
	v_pk_fma_f32 v[158:159], v[180:181], v[158:159], s[48:49] op_sel_hi:[1,1,0]
	v_max_f32_e32 v152, 0, v152
	v_pk_mul_f32 v[158:159], v[180:181], v[158:159]
	v_max_f32_e32 v153, 0, v153
	v_pk_mul_f32 v[158:159], v[170:171], v[158:159]
	v_fma_f32 v176, |v172|, s38, 1.0
	v_fma_f32 v177, |v173|, s38, 1.0
	v_pk_mul_f32 v[178:179], v[172:173], v[172:173]
	v_rcp_f32_e32 v176, v176
	v_rcp_f32_e32 v177, v177
	v_pk_fma_f32 v[158:159], v[174:175], v[158:159], v[152:153] neg_lo:[1,0,0] neg_hi:[1,0,0]
	v_pk_fma_f32 v[174:175], v[176:177], s[40:41], v[146:147] op_sel_hi:[1,0,0]
	v_pk_mul_f32 v[178:179], v[178:179], s[50:51] op_sel_hi:[1,0]
	v_pk_fma_f32 v[174:175], v[176:177], v[174:175], s[44:45] op_sel_hi:[1,1,0]
	v_exp_f32_e32 v178, v178
	v_exp_f32_e32 v179, v179
	v_fma_f32 v180, |v156|, s38, 1.0
	v_fma_f32 v181, |v157|, s38, 1.0
	v_pk_fma_f32 v[174:175], v[176:177], v[174:175], s[46:47] op_sel_hi:[1,1,0]
	v_rcp_f32_e32 v180, v180
	v_rcp_f32_e32 v181, v181
	v_pk_fma_f32 v[174:175], v[176:177], v[174:175], s[48:49] op_sel_hi:[1,1,0]
	v_max_f32_e32 v170, 0, v172
	v_pk_mul_f32 v[174:175], v[176:177], v[174:175]
	v_pk_mul_f32 v[176:177], v[156:157], v[156:157]
	v_max_f32_e32 v171, 0, v173
	v_pk_mul_f32 v[174:175], v[178:179], v[174:175]
	v_max_f32_e32 v152, 0, v156
	v_fma_f32 v170, -|v172|, v174, v170
	v_fma_f32 v171, -|v173|, v175, v171
	v_pk_fma_f32 v[172:173], v[180:181], s[40:41], v[146:147] op_sel_hi:[1,0,0]
	v_pk_mul_f32 v[174:175], v[176:177], s[50:51] op_sel_hi:[1,0]
	v_pk_fma_f32 v[172:173], v[180:181], v[172:173], s[44:45] op_sel_hi:[1,1,0]
	v_exp_f32_e32 v174, v174
	v_exp_f32_e32 v175, v175
	v_pk_fma_f32 v[172:173], v[180:181], v[172:173], s[46:47] op_sel_hi:[1,1,0]
	v_max_f32_e32 v153, 0, v157
	v_pk_fma_f32 v[172:173], v[180:181], v[172:173], s[48:49] op_sel_hi:[1,1,0]
	s_nop 0
	v_pk_mul_f32 v[172:173], v[180:181], v[172:173]
	s_nop 0
	v_pk_mul_f32 v[172:173], v[174:175], v[172:173]
	s_nop 0
	v_fma_f32 v156, -|v156|, v172, v152
	v_fma_f32 v157, -|v157|, v173, v153
	v_cvt_pk_bf16_f32 v152, v154, v155
	v_cvt_pk_bf16_f32 v153, v158, v159
	v_cvt_pk_bf16_f32 v154, v170, v171
	v_pk_add_f32 v[172:173], v[64:65], 0 op_sel_hi:[1,0]
	v_cvt_pk_bf16_f32 v155, v156, v157
	global_store_dwordx4 v[150:151], v[152:155], off
	v_pk_add_f32 v[156:157], v[66:67], 0 op_sel_hi:[1,0]
	s_nop 0
	v_pk_add_f32 v[154:155], v[68:69], 0 op_sel_hi:[1,0]
	v_pk_add_f32 v[152:153], v[70:71], 0 op_sel_hi:[1,0]
	v_fma_f32 v170, |v154|, s38, 1.0
	v_fma_f32 v171, |v155|, s38, 1.0
	v_pk_mul_f32 v[178:179], v[154:155], v[154:155]
	v_rcp_f32_e32 v170, v170
	v_rcp_f32_e32 v171, v171
	v_pk_mul_f32 v[178:179], v[178:179], s[50:51] op_sel_hi:[1,0]
	v_pk_fma_f32 v[176:177], v[170:171], s[40:41], v[146:147] op_sel_hi:[1,0,0]
	v_exp_f32_e32 v178, v178
	v_pk_fma_f32 v[176:177], v[170:171], v[176:177], s[44:45] op_sel_hi:[1,1,0]
	v_exp_f32_e32 v179, v179
	v_fma_f32 v180, |v152|, s38, 1.0
	v_fma_f32 v181, |v153|, s38, 1.0
	v_pk_fma_f32 v[176:177], v[170:171], v[176:177], s[46:47] op_sel_hi:[1,1,0]
	v_rcp_f32_e32 v180, v180
	v_rcp_f32_e32 v181, v181
	v_pk_fma_f32 v[176:177], v[170:171], v[176:177], s[48:49] op_sel_hi:[1,1,0]
	v_max_f32_e32 v158, 0, v154
	v_pk_mul_f32 v[170:171], v[170:171], v[176:177]
	v_pk_mul_f32 v[176:177], v[152:153], v[152:153]
	v_max_f32_e32 v159, 0, v155
	v_pk_mul_f32 v[170:171], v[178:179], v[170:171]
	v_max_f32_e32 v174, 0, v152
	v_fma_f32 v154, -|v154|, v170, v158
	v_fma_f32 v155, -|v155|, v171, v159
	v_pk_fma_f32 v[158:159], v[180:181], s[40:41], v[146:147] op_sel_hi:[1,0,0]
	v_pk_mul_f32 v[170:171], v[176:177], s[50:51] op_sel_hi:[1,0]
	v_pk_fma_f32 v[158:159], v[180:181], v[158:159], s[44:45] op_sel_hi:[1,1,0]
	v_exp_f32_e32 v170, v170
	v_exp_f32_e32 v171, v171
	v_pk_fma_f32 v[158:159], v[180:181], v[158:159], s[46:47] op_sel_hi:[1,1,0]
	v_max_f32_e32 v175, 0, v153
	v_pk_fma_f32 v[158:159], v[180:181], v[158:159], s[48:49] op_sel_hi:[1,1,0]
	v_pk_mul_f32 v[178:179], v[172:173], v[172:173]
	v_pk_mul_f32 v[158:159], v[180:181], v[158:159]
	v_pk_mul_f32 v[178:179], v[178:179], s[50:51] op_sel_hi:[1,0]
	v_pk_mul_f32 v[158:159], v[170:171], v[158:159]
	v_fma_f32 v176, |v172|, s38, 1.0
	v_fma_f32 v177, |v173|, s38, 1.0
	v_fma_f32 v158, -|v152|, v158, v174
	v_fma_f32 v159, -|v153|, v159, v175
	v_rcp_f32_e32 v176, v176
	v_rcp_f32_e32 v177, v177
	v_exp_f32_e32 v178, v178
	v_pk_fma_f32 v[174:175], v[176:177], s[40:41], v[146:147] op_sel_hi:[1,0,0]
	v_exp_f32_e32 v179, v179
	v_pk_fma_f32 v[174:175], v[176:177], v[174:175], s[44:45] op_sel_hi:[1,1,0]
	v_fma_f32 v180, |v156|, s38, 1.0
	v_fma_f32 v181, |v157|, s38, 1.0
	v_pk_fma_f32 v[174:175], v[176:177], v[174:175], s[46:47] op_sel_hi:[1,1,0]
	v_rcp_f32_e32 v180, v180
	v_rcp_f32_e32 v181, v181
	v_pk_fma_f32 v[174:175], v[176:177], v[174:175], s[48:49] op_sel_hi:[1,1,0]
	v_max_f32_e32 v170, 0, v172
	v_pk_mul_f32 v[174:175], v[176:177], v[174:175]
	v_pk_mul_f32 v[176:177], v[156:157], v[156:157]
	v_max_f32_e32 v171, 0, v173
	v_pk_mul_f32 v[174:175], v[178:179], v[174:175]
	v_max_f32_e32 v152, 0, v156
	v_fma_f32 v170, -|v172|, v174, v170
	v_fma_f32 v171, -|v173|, v175, v171
	v_pk_fma_f32 v[172:173], v[180:181], s[40:41], v[146:147] op_sel_hi:[1,0,0]
	v_pk_mul_f32 v[174:175], v[176:177], s[50:51] op_sel_hi:[1,0]
	v_pk_fma_f32 v[172:173], v[180:181], v[172:173], s[44:45] op_sel_hi:[1,1,0]
	v_exp_f32_e32 v174, v174
	v_exp_f32_e32 v175, v175
	v_pk_fma_f32 v[172:173], v[180:181], v[172:173], s[46:47] op_sel_hi:[1,1,0]
	v_max_f32_e32 v153, 0, v157
	v_pk_fma_f32 v[172:173], v[180:181], v[172:173], s[48:49] op_sel_hi:[1,1,0]
	s_nop 0
	v_pk_mul_f32 v[172:173], v[180:181], v[172:173]
	s_nop 0
	v_pk_mul_f32 v[172:173], v[174:175], v[172:173]
	s_nop 0
	v_fma_f32 v156, -|v156|, v172, v152
	v_fma_f32 v157, -|v157|, v173, v153
	v_cvt_pk_bf16_f32 v152, v154, v155
	v_cvt_pk_bf16_f32 v153, v158, v159
	v_cvt_pk_bf16_f32 v154, v170, v171
	v_pk_add_f32 v[172:173], v[56:57], 0 op_sel_hi:[1,0]
	v_cvt_pk_bf16_f32 v155, v156, v157
	global_store_dwordx4 v[150:151], v[152:155], off offset:256
	v_pk_add_f32 v[156:157], v[58:59], 0 op_sel_hi:[1,0]
	v_lshl_add_u64 v[150:151], v[148:149], 0, s[0:1]
	v_pk_add_f32 v[154:155], v[60:61], 0 op_sel_hi:[1,0]
	v_pk_add_f32 v[152:153], v[62:63], 0 op_sel_hi:[1,0]
	v_fma_f32 v170, |v154|, s38, 1.0
	v_fma_f32 v171, |v155|, s38, 1.0
	v_pk_mul_f32 v[178:179], v[154:155], v[154:155]
	v_rcp_f32_e32 v170, v170
	v_rcp_f32_e32 v171, v171
	v_pk_mul_f32 v[178:179], v[178:179], s[50:51] op_sel_hi:[1,0]
	v_pk_fma_f32 v[176:177], v[170:171], s[40:41], v[146:147] op_sel_hi:[1,0,0]
	v_exp_f32_e32 v178, v178
	v_pk_fma_f32 v[176:177], v[170:171], v[176:177], s[44:45] op_sel_hi:[1,1,0]
	v_exp_f32_e32 v179, v179
	v_fma_f32 v180, |v152|, s38, 1.0
	v_fma_f32 v181, |v153|, s38, 1.0
	v_pk_fma_f32 v[176:177], v[170:171], v[176:177], s[46:47] op_sel_hi:[1,1,0]
	v_rcp_f32_e32 v180, v180
	v_rcp_f32_e32 v181, v181
	v_pk_fma_f32 v[176:177], v[170:171], v[176:177], s[48:49] op_sel_hi:[1,1,0]
	v_max_f32_e32 v158, 0, v154
	v_pk_mul_f32 v[170:171], v[170:171], v[176:177]
	v_pk_mul_f32 v[176:177], v[152:153], v[152:153]
	v_max_f32_e32 v159, 0, v155
	v_pk_mul_f32 v[170:171], v[178:179], v[170:171]
	v_max_f32_e32 v174, 0, v152
	v_fma_f32 v154, -|v154|, v170, v158
	v_fma_f32 v155, -|v155|, v171, v159
	v_pk_fma_f32 v[158:159], v[180:181], s[40:41], v[146:147] op_sel_hi:[1,0,0]
	v_pk_mul_f32 v[170:171], v[176:177], s[50:51] op_sel_hi:[1,0]
	v_pk_fma_f32 v[158:159], v[180:181], v[158:159], s[44:45] op_sel_hi:[1,1,0]
	v_exp_f32_e32 v170, v170
	v_exp_f32_e32 v171, v171
	v_pk_fma_f32 v[158:159], v[180:181], v[158:159], s[46:47] op_sel_hi:[1,1,0]
	v_max_f32_e32 v175, 0, v153
	v_pk_fma_f32 v[158:159], v[180:181], v[158:159], s[48:49] op_sel_hi:[1,1,0]
	v_pk_mul_f32 v[178:179], v[172:173], v[172:173]
	v_pk_mul_f32 v[158:159], v[180:181], v[158:159]
	v_pk_mul_f32 v[178:179], v[178:179], s[50:51] op_sel_hi:[1,0]
	v_pk_mul_f32 v[158:159], v[170:171], v[158:159]
	v_fma_f32 v176, |v172|, s38, 1.0
	v_fma_f32 v177, |v173|, s38, 1.0
	v_fma_f32 v158, -|v152|, v158, v174
	v_fma_f32 v159, -|v153|, v159, v175
	v_rcp_f32_e32 v176, v176
	v_rcp_f32_e32 v177, v177
	v_exp_f32_e32 v178, v178
	v_pk_fma_f32 v[174:175], v[176:177], s[40:41], v[146:147] op_sel_hi:[1,0,0]
	v_exp_f32_e32 v179, v179
	v_pk_fma_f32 v[174:175], v[176:177], v[174:175], s[44:45] op_sel_hi:[1,1,0]
	v_fma_f32 v180, |v156|, s38, 1.0
	v_fma_f32 v181, |v157|, s38, 1.0
	v_pk_fma_f32 v[174:175], v[176:177], v[174:175], s[46:47] op_sel_hi:[1,1,0]
	v_rcp_f32_e32 v180, v180
	v_rcp_f32_e32 v181, v181
	v_pk_fma_f32 v[174:175], v[176:177], v[174:175], s[48:49] op_sel_hi:[1,1,0]
	v_max_f32_e32 v170, 0, v172
	v_pk_mul_f32 v[174:175], v[176:177], v[174:175]
	v_pk_mul_f32 v[176:177], v[156:157], v[156:157]
	v_max_f32_e32 v171, 0, v173
	v_pk_mul_f32 v[174:175], v[178:179], v[174:175]
	v_max_f32_e32 v152, 0, v156
	v_fma_f32 v170, -|v172|, v174, v170
	v_fma_f32 v171, -|v173|, v175, v171
	v_pk_fma_f32 v[172:173], v[180:181], s[40:41], v[146:147] op_sel_hi:[1,0,0]
	v_pk_mul_f32 v[174:175], v[176:177], s[50:51] op_sel_hi:[1,0]
	v_pk_fma_f32 v[172:173], v[180:181], v[172:173], s[44:45] op_sel_hi:[1,1,0]
	v_exp_f32_e32 v174, v174
	v_exp_f32_e32 v175, v175
	v_pk_fma_f32 v[172:173], v[180:181], v[172:173], s[46:47] op_sel_hi:[1,1,0]
	v_max_f32_e32 v153, 0, v157
	v_pk_fma_f32 v[172:173], v[180:181], v[172:173], s[48:49] op_sel_hi:[1,1,0]
	s_mov_b32 s0, 0x40000
	v_pk_mul_f32 v[172:173], v[180:181], v[172:173]
	s_nop 0
	v_pk_mul_f32 v[172:173], v[174:175], v[172:173]
	s_nop 0
	v_fma_f32 v156, -|v156|, v172, v152
	v_fma_f32 v157, -|v157|, v173, v153
	v_cvt_pk_bf16_f32 v152, v154, v155
	v_cvt_pk_bf16_f32 v153, v158, v159
	v_cvt_pk_bf16_f32 v154, v170, v171
	v_pk_add_f32 v[172:173], v[48:49], 0 op_sel_hi:[1,0]
	v_cvt_pk_bf16_f32 v155, v156, v157
	v_add_co_u32_e32 v156, vcc, s0, v148
	s_mov_b64 s[0:1], 0x48000
	s_nop 0
	v_addc_co_u32_e32 v157, vcc, 0, v149, vcc
	global_store_dwordx4 v[156:157], v[152:155], off
	v_pk_add_f32 v[156:157], v[50:51], 0 op_sel_hi:[1,0]
	s_nop 0
	v_pk_add_f32 v[154:155], v[52:53], 0 op_sel_hi:[1,0]
	v_pk_add_f32 v[152:153], v[54:55], 0 op_sel_hi:[1,0]
	v_fma_f32 v170, |v154|, s38, 1.0
	v_fma_f32 v171, |v155|, s38, 1.0
	v_pk_mul_f32 v[178:179], v[154:155], v[154:155]
	v_rcp_f32_e32 v170, v170
	v_rcp_f32_e32 v171, v171
	v_pk_mul_f32 v[178:179], v[178:179], s[50:51] op_sel_hi:[1,0]
	v_pk_fma_f32 v[176:177], v[170:171], s[40:41], v[146:147] op_sel_hi:[1,0,0]
	v_exp_f32_e32 v178, v178
	v_pk_fma_f32 v[176:177], v[170:171], v[176:177], s[44:45] op_sel_hi:[1,1,0]
	v_exp_f32_e32 v179, v179
	v_fma_f32 v180, |v152|, s38, 1.0
	v_fma_f32 v181, |v153|, s38, 1.0
	v_pk_fma_f32 v[176:177], v[170:171], v[176:177], s[46:47] op_sel_hi:[1,1,0]
	v_rcp_f32_e32 v180, v180
	v_rcp_f32_e32 v181, v181
	v_pk_fma_f32 v[176:177], v[170:171], v[176:177], s[48:49] op_sel_hi:[1,1,0]
	v_max_f32_e32 v158, 0, v154
	v_pk_mul_f32 v[170:171], v[170:171], v[176:177]
	v_pk_mul_f32 v[176:177], v[152:153], v[152:153]
	v_max_f32_e32 v159, 0, v155
	v_pk_mul_f32 v[170:171], v[178:179], v[170:171]
	v_max_f32_e32 v174, 0, v152
	v_fma_f32 v154, -|v154|, v170, v158
	v_fma_f32 v155, -|v155|, v171, v159
	v_pk_fma_f32 v[158:159], v[180:181], s[40:41], v[146:147] op_sel_hi:[1,0,0]
	v_pk_mul_f32 v[170:171], v[176:177], s[50:51] op_sel_hi:[1,0]
	v_pk_fma_f32 v[158:159], v[180:181], v[158:159], s[44:45] op_sel_hi:[1,1,0]
	v_exp_f32_e32 v170, v170
	v_exp_f32_e32 v171, v171
	v_pk_fma_f32 v[158:159], v[180:181], v[158:159], s[46:47] op_sel_hi:[1,1,0]
	v_max_f32_e32 v175, 0, v153
	v_pk_fma_f32 v[158:159], v[180:181], v[158:159], s[48:49] op_sel_hi:[1,1,0]
	v_pk_mul_f32 v[178:179], v[172:173], v[172:173]
	v_pk_mul_f32 v[158:159], v[180:181], v[158:159]
	v_pk_mul_f32 v[178:179], v[178:179], s[50:51] op_sel_hi:[1,0]
	v_pk_mul_f32 v[158:159], v[170:171], v[158:159]
	v_fma_f32 v176, |v172|, s38, 1.0
	v_fma_f32 v177, |v173|, s38, 1.0
	v_fma_f32 v158, -|v152|, v158, v174
	v_fma_f32 v159, -|v153|, v159, v175
	v_rcp_f32_e32 v176, v176
	v_rcp_f32_e32 v177, v177
	v_exp_f32_e32 v178, v178
	v_pk_fma_f32 v[174:175], v[176:177], s[40:41], v[146:147] op_sel_hi:[1,0,0]
	v_exp_f32_e32 v179, v179
	v_pk_fma_f32 v[174:175], v[176:177], v[174:175], s[44:45] op_sel_hi:[1,1,0]
	v_fma_f32 v180, |v156|, s38, 1.0
	v_fma_f32 v181, |v157|, s38, 1.0
	v_pk_fma_f32 v[174:175], v[176:177], v[174:175], s[46:47] op_sel_hi:[1,1,0]
	v_rcp_f32_e32 v180, v180
	v_rcp_f32_e32 v181, v181
	v_pk_fma_f32 v[174:175], v[176:177], v[174:175], s[48:49] op_sel_hi:[1,1,0]
	v_max_f32_e32 v170, 0, v172
	v_pk_mul_f32 v[174:175], v[176:177], v[174:175]
	v_pk_mul_f32 v[176:177], v[156:157], v[156:157]
	v_max_f32_e32 v171, 0, v173
	v_pk_mul_f32 v[174:175], v[178:179], v[174:175]
	v_max_f32_e32 v152, 0, v156
	v_fma_f32 v170, -|v172|, v174, v170
	v_fma_f32 v171, -|v173|, v175, v171
	v_pk_fma_f32 v[172:173], v[180:181], s[40:41], v[146:147] op_sel_hi:[1,0,0]
	v_pk_mul_f32 v[174:175], v[176:177], s[50:51] op_sel_hi:[1,0]
	v_pk_fma_f32 v[172:173], v[180:181], v[172:173], s[44:45] op_sel_hi:[1,1,0]
	v_exp_f32_e32 v174, v174
	v_exp_f32_e32 v175, v175
	v_pk_fma_f32 v[172:173], v[180:181], v[172:173], s[46:47] op_sel_hi:[1,1,0]
	v_max_f32_e32 v153, 0, v157
	v_pk_fma_f32 v[172:173], v[180:181], v[172:173], s[48:49] op_sel_hi:[1,1,0]
	s_nop 0
	v_pk_mul_f32 v[172:173], v[180:181], v[172:173]
	s_nop 0
	v_pk_mul_f32 v[172:173], v[174:175], v[172:173]
	s_nop 0
	v_fma_f32 v156, -|v156|, v172, v152
	v_fma_f32 v157, -|v157|, v173, v153
	v_cvt_pk_bf16_f32 v152, v154, v155
	v_cvt_pk_bf16_f32 v153, v158, v159
	v_cvt_pk_bf16_f32 v154, v170, v171
	v_pk_add_f32 v[172:173], v[40:41], 0 op_sel_hi:[1,0]
	v_cvt_pk_bf16_f32 v155, v156, v157
	global_store_dwordx4 v[150:151], v[152:155], off offset:256
	v_pk_add_f32 v[156:157], v[42:43], 0 op_sel_hi:[1,0]
	v_lshl_add_u64 v[150:151], v[148:149], 0, s[0:1]
	v_pk_add_f32 v[154:155], v[44:45], 0 op_sel_hi:[1,0]
	v_pk_add_f32 v[152:153], v[46:47], 0 op_sel_hi:[1,0]
	v_fma_f32 v170, |v154|, s38, 1.0
	v_fma_f32 v171, |v155|, s38, 1.0
	v_pk_mul_f32 v[178:179], v[154:155], v[154:155]
	v_rcp_f32_e32 v170, v170
	v_rcp_f32_e32 v171, v171
	v_pk_mul_f32 v[178:179], v[178:179], s[50:51] op_sel_hi:[1,0]
	v_pk_fma_f32 v[176:177], v[170:171], s[40:41], v[146:147] op_sel_hi:[1,0,0]
	v_exp_f32_e32 v178, v178
	v_pk_fma_f32 v[176:177], v[170:171], v[176:177], s[44:45] op_sel_hi:[1,1,0]
	v_exp_f32_e32 v179, v179
	v_fma_f32 v180, |v152|, s38, 1.0
	v_fma_f32 v181, |v153|, s38, 1.0
	v_pk_fma_f32 v[176:177], v[170:171], v[176:177], s[46:47] op_sel_hi:[1,1,0]
	v_rcp_f32_e32 v180, v180
	v_rcp_f32_e32 v181, v181
	v_pk_fma_f32 v[176:177], v[170:171], v[176:177], s[48:49] op_sel_hi:[1,1,0]
	v_max_f32_e32 v158, 0, v154
	v_pk_mul_f32 v[170:171], v[170:171], v[176:177]
	v_pk_mul_f32 v[176:177], v[152:153], v[152:153]
	v_max_f32_e32 v159, 0, v155
	v_pk_mul_f32 v[170:171], v[178:179], v[170:171]
	v_max_f32_e32 v174, 0, v152
	v_fma_f32 v154, -|v154|, v170, v158
	v_fma_f32 v155, -|v155|, v171, v159
	v_pk_fma_f32 v[158:159], v[180:181], s[40:41], v[146:147] op_sel_hi:[1,0,0]
	v_pk_mul_f32 v[170:171], v[176:177], s[50:51] op_sel_hi:[1,0]
	v_pk_fma_f32 v[158:159], v[180:181], v[158:159], s[44:45] op_sel_hi:[1,1,0]
	v_exp_f32_e32 v170, v170
	v_exp_f32_e32 v171, v171
	v_pk_fma_f32 v[158:159], v[180:181], v[158:159], s[46:47] op_sel_hi:[1,1,0]
	v_max_f32_e32 v175, 0, v153
	v_pk_fma_f32 v[158:159], v[180:181], v[158:159], s[48:49] op_sel_hi:[1,1,0]
	v_pk_mul_f32 v[178:179], v[172:173], v[172:173]
	v_pk_mul_f32 v[158:159], v[180:181], v[158:159]
	v_pk_mul_f32 v[178:179], v[178:179], s[50:51] op_sel_hi:[1,0]
	v_pk_mul_f32 v[158:159], v[170:171], v[158:159]
	v_fma_f32 v176, |v172|, s38, 1.0
	v_fma_f32 v177, |v173|, s38, 1.0
	v_fma_f32 v158, -|v152|, v158, v174
	v_fma_f32 v159, -|v153|, v159, v175
	v_rcp_f32_e32 v176, v176
	v_rcp_f32_e32 v177, v177
	v_exp_f32_e32 v178, v178
	v_pk_fma_f32 v[174:175], v[176:177], s[40:41], v[146:147] op_sel_hi:[1,0,0]
	v_exp_f32_e32 v179, v179
	v_pk_fma_f32 v[174:175], v[176:177], v[174:175], s[44:45] op_sel_hi:[1,1,0]
	v_fma_f32 v180, |v156|, s38, 1.0
	v_fma_f32 v181, |v157|, s38, 1.0
	v_pk_fma_f32 v[174:175], v[176:177], v[174:175], s[46:47] op_sel_hi:[1,1,0]
	v_rcp_f32_e32 v180, v180
	v_rcp_f32_e32 v181, v181
	v_pk_fma_f32 v[174:175], v[176:177], v[174:175], s[48:49] op_sel_hi:[1,1,0]
	v_max_f32_e32 v170, 0, v172
	v_pk_mul_f32 v[174:175], v[176:177], v[174:175]
	v_pk_mul_f32 v[176:177], v[156:157], v[156:157]
	v_max_f32_e32 v171, 0, v173
	v_pk_mul_f32 v[174:175], v[178:179], v[174:175]
	v_max_f32_e32 v152, 0, v156
	v_fma_f32 v170, -|v172|, v174, v170
	v_fma_f32 v171, -|v173|, v175, v171
	v_pk_fma_f32 v[172:173], v[180:181], s[40:41], v[146:147] op_sel_hi:[1,0,0]
	v_pk_mul_f32 v[174:175], v[176:177], s[50:51] op_sel_hi:[1,0]
	v_pk_fma_f32 v[172:173], v[180:181], v[172:173], s[44:45] op_sel_hi:[1,1,0]
	v_exp_f32_e32 v174, v174
	v_exp_f32_e32 v175, v175
	v_pk_fma_f32 v[172:173], v[180:181], v[172:173], s[46:47] op_sel_hi:[1,1,0]
	v_max_f32_e32 v153, 0, v157
	v_pk_fma_f32 v[172:173], v[180:181], v[172:173], s[48:49] op_sel_hi:[1,1,0]
	s_mov_b32 s0, 0x48000
	v_pk_mul_f32 v[172:173], v[180:181], v[172:173]
	s_nop 0
	v_pk_mul_f32 v[172:173], v[174:175], v[172:173]
	s_nop 0
	v_fma_f32 v156, -|v156|, v172, v152
	v_fma_f32 v157, -|v157|, v173, v153
	v_cvt_pk_bf16_f32 v152, v154, v155
	v_cvt_pk_bf16_f32 v153, v158, v159
	v_cvt_pk_bf16_f32 v154, v170, v171
	v_pk_add_f32 v[172:173], v[32:33], 0 op_sel_hi:[1,0]
	v_cvt_pk_bf16_f32 v155, v156, v157
	v_add_co_u32_e32 v156, vcc, s0, v148
	s_mov_b64 s[0:1], 0x50000
	s_nop 0
	v_addc_co_u32_e32 v157, vcc, 0, v149, vcc
	global_store_dwordx4 v[156:157], v[152:155], off
	v_pk_add_f32 v[156:157], v[34:35], 0 op_sel_hi:[1,0]
	s_nop 0
	v_pk_add_f32 v[154:155], v[36:37], 0 op_sel_hi:[1,0]
	v_pk_add_f32 v[152:153], v[38:39], 0 op_sel_hi:[1,0]
	v_fma_f32 v170, |v154|, s38, 1.0
	v_fma_f32 v171, |v155|, s38, 1.0
	v_pk_mul_f32 v[178:179], v[154:155], v[154:155]
	v_rcp_f32_e32 v170, v170
	v_rcp_f32_e32 v171, v171
	v_pk_mul_f32 v[178:179], v[178:179], s[50:51] op_sel_hi:[1,0]
	v_pk_fma_f32 v[176:177], v[170:171], s[40:41], v[146:147] op_sel_hi:[1,0,0]
	v_exp_f32_e32 v178, v178
	v_pk_fma_f32 v[176:177], v[170:171], v[176:177], s[44:45] op_sel_hi:[1,1,0]
	v_exp_f32_e32 v179, v179
	v_fma_f32 v180, |v152|, s38, 1.0
	v_fma_f32 v181, |v153|, s38, 1.0
	v_pk_fma_f32 v[176:177], v[170:171], v[176:177], s[46:47] op_sel_hi:[1,1,0]
	v_rcp_f32_e32 v180, v180
	v_rcp_f32_e32 v181, v181
	v_pk_fma_f32 v[176:177], v[170:171], v[176:177], s[48:49] op_sel_hi:[1,1,0]
	v_max_f32_e32 v158, 0, v154
	v_pk_mul_f32 v[170:171], v[170:171], v[176:177]
	v_pk_mul_f32 v[176:177], v[152:153], v[152:153]
	v_max_f32_e32 v159, 0, v155
	v_pk_mul_f32 v[170:171], v[178:179], v[170:171]
	v_max_f32_e32 v174, 0, v152
	v_fma_f32 v154, -|v154|, v170, v158
	v_fma_f32 v155, -|v155|, v171, v159
	v_pk_fma_f32 v[158:159], v[180:181], s[40:41], v[146:147] op_sel_hi:[1,0,0]
	v_pk_mul_f32 v[170:171], v[176:177], s[50:51] op_sel_hi:[1,0]
	v_pk_fma_f32 v[158:159], v[180:181], v[158:159], s[44:45] op_sel_hi:[1,1,0]
	v_exp_f32_e32 v170, v170
	v_exp_f32_e32 v171, v171
	v_pk_fma_f32 v[158:159], v[180:181], v[158:159], s[46:47] op_sel_hi:[1,1,0]
	v_max_f32_e32 v175, 0, v153
	v_pk_fma_f32 v[158:159], v[180:181], v[158:159], s[48:49] op_sel_hi:[1,1,0]
	v_pk_mul_f32 v[178:179], v[172:173], v[172:173]
	v_pk_mul_f32 v[158:159], v[180:181], v[158:159]
	v_pk_mul_f32 v[178:179], v[178:179], s[50:51] op_sel_hi:[1,0]
	v_pk_mul_f32 v[158:159], v[170:171], v[158:159]
	v_fma_f32 v176, |v172|, s38, 1.0
	v_fma_f32 v177, |v173|, s38, 1.0
	v_fma_f32 v158, -|v152|, v158, v174
	v_fma_f32 v159, -|v153|, v159, v175
	v_rcp_f32_e32 v176, v176
	v_rcp_f32_e32 v177, v177
	v_exp_f32_e32 v178, v178
	v_pk_fma_f32 v[174:175], v[176:177], s[40:41], v[146:147] op_sel_hi:[1,0,0]
	v_exp_f32_e32 v179, v179
	v_pk_fma_f32 v[174:175], v[176:177], v[174:175], s[44:45] op_sel_hi:[1,1,0]
	v_fma_f32 v180, |v156|, s38, 1.0
	v_fma_f32 v181, |v157|, s38, 1.0
	v_pk_fma_f32 v[174:175], v[176:177], v[174:175], s[46:47] op_sel_hi:[1,1,0]
	v_rcp_f32_e32 v180, v180
	v_rcp_f32_e32 v181, v181
	v_pk_fma_f32 v[174:175], v[176:177], v[174:175], s[48:49] op_sel_hi:[1,1,0]
	v_max_f32_e32 v170, 0, v172
	v_pk_mul_f32 v[174:175], v[176:177], v[174:175]
	v_pk_mul_f32 v[176:177], v[156:157], v[156:157]
	v_max_f32_e32 v171, 0, v173
	v_pk_mul_f32 v[174:175], v[178:179], v[174:175]
	v_max_f32_e32 v152, 0, v156
	v_fma_f32 v170, -|v172|, v174, v170
	v_fma_f32 v171, -|v173|, v175, v171
	v_pk_fma_f32 v[172:173], v[180:181], s[40:41], v[146:147] op_sel_hi:[1,0,0]
	v_pk_mul_f32 v[174:175], v[176:177], s[50:51] op_sel_hi:[1,0]
	v_pk_fma_f32 v[172:173], v[180:181], v[172:173], s[44:45] op_sel_hi:[1,1,0]
	v_exp_f32_e32 v174, v174
	v_exp_f32_e32 v175, v175
	v_pk_fma_f32 v[172:173], v[180:181], v[172:173], s[46:47] op_sel_hi:[1,1,0]
	v_max_f32_e32 v153, 0, v157
	v_pk_fma_f32 v[172:173], v[180:181], v[172:173], s[48:49] op_sel_hi:[1,1,0]
	s_nop 0
	v_pk_mul_f32 v[172:173], v[180:181], v[172:173]
	s_nop 0
	v_pk_mul_f32 v[172:173], v[174:175], v[172:173]
	s_nop 0
	v_fma_f32 v156, -|v156|, v172, v152
	v_fma_f32 v157, -|v157|, v173, v153
	v_cvt_pk_bf16_f32 v152, v154, v155
	v_cvt_pk_bf16_f32 v153, v158, v159
	v_cvt_pk_bf16_f32 v154, v170, v171
	v_pk_add_f32 v[172:173], v[24:25], 0 op_sel_hi:[1,0]
	v_cvt_pk_bf16_f32 v155, v156, v157
	global_store_dwordx4 v[150:151], v[152:155], off offset:256
	v_pk_add_f32 v[156:157], v[26:27], 0 op_sel_hi:[1,0]
	v_lshl_add_u64 v[150:151], v[148:149], 0, s[0:1]
	v_pk_add_f32 v[154:155], v[28:29], 0 op_sel_hi:[1,0]
	v_pk_add_f32 v[152:153], v[30:31], 0 op_sel_hi:[1,0]
	v_fma_f32 v170, |v154|, s38, 1.0
	v_fma_f32 v171, |v155|, s38, 1.0
	v_pk_mul_f32 v[178:179], v[154:155], v[154:155]
	v_rcp_f32_e32 v170, v170
	v_rcp_f32_e32 v171, v171
	v_pk_mul_f32 v[178:179], v[178:179], s[50:51] op_sel_hi:[1,0]
	v_pk_fma_f32 v[176:177], v[170:171], s[40:41], v[146:147] op_sel_hi:[1,0,0]
	v_exp_f32_e32 v178, v178
	v_pk_fma_f32 v[176:177], v[170:171], v[176:177], s[44:45] op_sel_hi:[1,1,0]
	v_exp_f32_e32 v179, v179
	v_fma_f32 v180, |v152|, s38, 1.0
	v_fma_f32 v181, |v153|, s38, 1.0
	v_pk_fma_f32 v[176:177], v[170:171], v[176:177], s[46:47] op_sel_hi:[1,1,0]
	v_rcp_f32_e32 v180, v180
	v_rcp_f32_e32 v181, v181
	v_pk_fma_f32 v[176:177], v[170:171], v[176:177], s[48:49] op_sel_hi:[1,1,0]
	v_max_f32_e32 v158, 0, v154
	v_pk_mul_f32 v[170:171], v[170:171], v[176:177]
	v_pk_mul_f32 v[176:177], v[152:153], v[152:153]
	v_max_f32_e32 v159, 0, v155
	v_pk_mul_f32 v[170:171], v[178:179], v[170:171]
	v_max_f32_e32 v174, 0, v152
	v_fma_f32 v154, -|v154|, v170, v158
	v_fma_f32 v155, -|v155|, v171, v159
	v_pk_fma_f32 v[158:159], v[180:181], s[40:41], v[146:147] op_sel_hi:[1,0,0]
	v_pk_mul_f32 v[170:171], v[176:177], s[50:51] op_sel_hi:[1,0]
	v_pk_fma_f32 v[158:159], v[180:181], v[158:159], s[44:45] op_sel_hi:[1,1,0]
	v_exp_f32_e32 v170, v170
	v_exp_f32_e32 v171, v171
	v_pk_fma_f32 v[158:159], v[180:181], v[158:159], s[46:47] op_sel_hi:[1,1,0]
	v_max_f32_e32 v175, 0, v153
	v_pk_fma_f32 v[158:159], v[180:181], v[158:159], s[48:49] op_sel_hi:[1,1,0]
	v_pk_mul_f32 v[178:179], v[172:173], v[172:173]
	v_pk_mul_f32 v[158:159], v[180:181], v[158:159]
	v_pk_mul_f32 v[178:179], v[178:179], s[50:51] op_sel_hi:[1,0]
	v_pk_mul_f32 v[158:159], v[170:171], v[158:159]
	v_fma_f32 v176, |v172|, s38, 1.0
	v_fma_f32 v177, |v173|, s38, 1.0
	v_fma_f32 v158, -|v152|, v158, v174
	v_fma_f32 v159, -|v153|, v159, v175
	v_rcp_f32_e32 v176, v176
	v_rcp_f32_e32 v177, v177
	v_exp_f32_e32 v178, v178
	v_pk_fma_f32 v[174:175], v[176:177], s[40:41], v[146:147] op_sel_hi:[1,0,0]
	v_exp_f32_e32 v179, v179
	v_pk_fma_f32 v[174:175], v[176:177], v[174:175], s[44:45] op_sel_hi:[1,1,0]
	v_fma_f32 v180, |v156|, s38, 1.0
	v_fma_f32 v181, |v157|, s38, 1.0
	v_pk_fma_f32 v[174:175], v[176:177], v[174:175], s[46:47] op_sel_hi:[1,1,0]
	v_rcp_f32_e32 v180, v180
	v_rcp_f32_e32 v181, v181
	v_pk_fma_f32 v[174:175], v[176:177], v[174:175], s[48:49] op_sel_hi:[1,1,0]
	v_max_f32_e32 v170, 0, v172
	v_pk_mul_f32 v[174:175], v[176:177], v[174:175]
	v_pk_mul_f32 v[176:177], v[156:157], v[156:157]
	v_max_f32_e32 v171, 0, v173
	v_pk_mul_f32 v[174:175], v[178:179], v[174:175]
	v_max_f32_e32 v152, 0, v156
	v_fma_f32 v170, -|v172|, v174, v170
	v_fma_f32 v171, -|v173|, v175, v171
	v_pk_fma_f32 v[172:173], v[180:181], s[40:41], v[146:147] op_sel_hi:[1,0,0]
	v_pk_mul_f32 v[174:175], v[176:177], s[50:51] op_sel_hi:[1,0]
	v_pk_fma_f32 v[172:173], v[180:181], v[172:173], s[44:45] op_sel_hi:[1,1,0]
	v_exp_f32_e32 v174, v174
	v_exp_f32_e32 v175, v175
	v_pk_fma_f32 v[172:173], v[180:181], v[172:173], s[46:47] op_sel_hi:[1,1,0]
	v_max_f32_e32 v153, 0, v157
	v_pk_fma_f32 v[172:173], v[180:181], v[172:173], s[48:49] op_sel_hi:[1,1,0]
	s_nop 0
	v_pk_mul_f32 v[172:173], v[180:181], v[172:173]
	s_nop 0
	v_pk_mul_f32 v[172:173], v[174:175], v[172:173]
	s_nop 0
	v_fma_f32 v156, -|v156|, v172, v152
	v_fma_f32 v157, -|v157|, v173, v153
	v_cvt_pk_bf16_f32 v152, v154, v155
	v_cvt_pk_bf16_f32 v153, v158, v159
	v_cvt_pk_bf16_f32 v154, v170, v171
	v_pk_add_f32 v[172:173], v[16:17], 0 op_sel_hi:[1,0]
	v_cvt_pk_bf16_f32 v155, v156, v157
	v_add_co_u32_e32 v156, vcc, s84, v148
	s_nop 1
	v_addc_co_u32_e32 v157, vcc, 0, v149, vcc
	global_store_dwordx4 v[156:157], v[152:155], off
	v_pk_add_f32 v[156:157], v[18:19], 0 op_sel_hi:[1,0]
	s_nop 0
	v_pk_add_f32 v[154:155], v[20:21], 0 op_sel_hi:[1,0]
	v_pk_add_f32 v[152:153], v[22:23], 0 op_sel_hi:[1,0]
	v_fma_f32 v170, |v154|, s38, 1.0
	v_fma_f32 v171, |v155|, s38, 1.0
	v_pk_mul_f32 v[178:179], v[154:155], v[154:155]
	v_rcp_f32_e32 v170, v170
	v_rcp_f32_e32 v171, v171
	v_pk_mul_f32 v[178:179], v[178:179], s[50:51] op_sel_hi:[1,0]
	v_pk_fma_f32 v[176:177], v[170:171], s[40:41], v[146:147] op_sel_hi:[1,0,0]
	v_exp_f32_e32 v178, v178
	v_pk_fma_f32 v[176:177], v[170:171], v[176:177], s[44:45] op_sel_hi:[1,1,0]
	v_exp_f32_e32 v179, v179
	v_fma_f32 v180, |v152|, s38, 1.0
	v_fma_f32 v181, |v153|, s38, 1.0
	v_pk_fma_f32 v[176:177], v[170:171], v[176:177], s[46:47] op_sel_hi:[1,1,0]
	v_rcp_f32_e32 v180, v180
	v_rcp_f32_e32 v181, v181
	v_pk_fma_f32 v[176:177], v[170:171], v[176:177], s[48:49] op_sel_hi:[1,1,0]
	v_max_f32_e32 v158, 0, v154
	v_pk_mul_f32 v[170:171], v[170:171], v[176:177]
	v_pk_mul_f32 v[176:177], v[152:153], v[152:153]
	v_max_f32_e32 v159, 0, v155
	v_pk_mul_f32 v[170:171], v[178:179], v[170:171]
	v_max_f32_e32 v174, 0, v152
	v_fma_f32 v154, -|v154|, v170, v158
	v_fma_f32 v155, -|v155|, v171, v159
	v_pk_fma_f32 v[158:159], v[180:181], s[40:41], v[146:147] op_sel_hi:[1,0,0]
	v_pk_mul_f32 v[170:171], v[176:177], s[50:51] op_sel_hi:[1,0]
	v_pk_fma_f32 v[158:159], v[180:181], v[158:159], s[44:45] op_sel_hi:[1,1,0]
	v_exp_f32_e32 v170, v170
	v_exp_f32_e32 v171, v171
	v_pk_fma_f32 v[158:159], v[180:181], v[158:159], s[46:47] op_sel_hi:[1,1,0]
	v_max_f32_e32 v175, 0, v153
	v_pk_fma_f32 v[158:159], v[180:181], v[158:159], s[48:49] op_sel_hi:[1,1,0]
	v_pk_mul_f32 v[178:179], v[172:173], v[172:173]
	v_pk_mul_f32 v[158:159], v[180:181], v[158:159]
	v_pk_mul_f32 v[178:179], v[178:179], s[50:51] op_sel_hi:[1,0]
	v_pk_mul_f32 v[158:159], v[170:171], v[158:159]
	v_fma_f32 v176, |v172|, s38, 1.0
	v_fma_f32 v177, |v173|, s38, 1.0
	v_fma_f32 v158, -|v152|, v158, v174
	v_fma_f32 v159, -|v153|, v159, v175
	v_rcp_f32_e32 v176, v176
	v_rcp_f32_e32 v177, v177
	v_exp_f32_e32 v178, v178
	v_pk_fma_f32 v[174:175], v[176:177], s[40:41], v[146:147] op_sel_hi:[1,0,0]
	v_exp_f32_e32 v179, v179
	v_pk_fma_f32 v[174:175], v[176:177], v[174:175], s[44:45] op_sel_hi:[1,1,0]
	v_fma_f32 v180, |v156|, s38, 1.0
	v_fma_f32 v181, |v157|, s38, 1.0
	v_pk_fma_f32 v[174:175], v[176:177], v[174:175], s[46:47] op_sel_hi:[1,1,0]
	v_rcp_f32_e32 v180, v180
	v_rcp_f32_e32 v181, v181
	v_pk_fma_f32 v[174:175], v[176:177], v[174:175], s[48:49] op_sel_hi:[1,1,0]
	v_max_f32_e32 v170, 0, v172
	v_pk_mul_f32 v[174:175], v[176:177], v[174:175]
	v_pk_mul_f32 v[176:177], v[156:157], v[156:157]
	v_max_f32_e32 v171, 0, v173
	v_pk_mul_f32 v[174:175], v[178:179], v[174:175]
	v_max_f32_e32 v152, 0, v156
	v_fma_f32 v170, -|v172|, v174, v170
	v_fma_f32 v171, -|v173|, v175, v171
	v_pk_fma_f32 v[172:173], v[180:181], s[40:41], v[146:147] op_sel_hi:[1,0,0]
	v_pk_mul_f32 v[174:175], v[176:177], s[50:51] op_sel_hi:[1,0]
	v_pk_fma_f32 v[172:173], v[180:181], v[172:173], s[44:45] op_sel_hi:[1,1,0]
	v_exp_f32_e32 v174, v174
	v_exp_f32_e32 v175, v175
	v_pk_fma_f32 v[172:173], v[180:181], v[172:173], s[46:47] op_sel_hi:[1,1,0]
	v_max_f32_e32 v153, 0, v157
	v_pk_fma_f32 v[172:173], v[180:181], v[172:173], s[48:49] op_sel_hi:[1,1,0]
	s_nop 0
	v_pk_mul_f32 v[172:173], v[180:181], v[172:173]
	s_nop 0
	v_pk_mul_f32 v[172:173], v[174:175], v[172:173]
	s_nop 0
	v_fma_f32 v156, -|v156|, v172, v152
	v_fma_f32 v157, -|v157|, v173, v153
	v_cvt_pk_bf16_f32 v152, v154, v155
	v_cvt_pk_bf16_f32 v153, v158, v159
	v_cvt_pk_bf16_f32 v154, v170, v171
	v_pk_add_f32 v[172:173], v[8:9], 0 op_sel_hi:[1,0]
	v_cvt_pk_bf16_f32 v155, v156, v157
	global_store_dwordx4 v[150:151], v[152:155], off offset:256
	v_pk_add_f32 v[156:157], v[10:11], 0 op_sel_hi:[1,0]
	v_lshl_add_u64 v[150:151], v[148:149], 0, s[52:53]
	v_pk_add_f32 v[154:155], v[12:13], 0 op_sel_hi:[1,0]
	v_pk_add_f32 v[152:153], v[14:15], 0 op_sel_hi:[1,0]
	v_fma_f32 v170, |v154|, s38, 1.0
	v_fma_f32 v171, |v155|, s38, 1.0
	v_pk_mul_f32 v[178:179], v[154:155], v[154:155]
	v_rcp_f32_e32 v170, v170
	v_rcp_f32_e32 v171, v171
	v_pk_mul_f32 v[178:179], v[178:179], s[50:51] op_sel_hi:[1,0]
	v_pk_fma_f32 v[176:177], v[170:171], s[40:41], v[146:147] op_sel_hi:[1,0,0]
	v_exp_f32_e32 v178, v178
	v_pk_fma_f32 v[176:177], v[170:171], v[176:177], s[44:45] op_sel_hi:[1,1,0]
	v_exp_f32_e32 v179, v179
	v_fma_f32 v180, |v152|, s38, 1.0
	v_fma_f32 v181, |v153|, s38, 1.0
	v_pk_fma_f32 v[176:177], v[170:171], v[176:177], s[46:47] op_sel_hi:[1,1,0]
	v_rcp_f32_e32 v180, v180
	v_rcp_f32_e32 v181, v181
	v_pk_fma_f32 v[176:177], v[170:171], v[176:177], s[48:49] op_sel_hi:[1,1,0]
	v_max_f32_e32 v158, 0, v154
	v_pk_mul_f32 v[170:171], v[170:171], v[176:177]
	v_pk_mul_f32 v[176:177], v[152:153], v[152:153]
	v_max_f32_e32 v159, 0, v155
	v_pk_mul_f32 v[170:171], v[178:179], v[170:171]
	v_max_f32_e32 v174, 0, v152
	v_fma_f32 v154, -|v154|, v170, v158
	v_fma_f32 v155, -|v155|, v171, v159
	v_pk_fma_f32 v[158:159], v[180:181], s[40:41], v[146:147] op_sel_hi:[1,0,0]
	v_pk_mul_f32 v[170:171], v[176:177], s[50:51] op_sel_hi:[1,0]
	v_pk_fma_f32 v[158:159], v[180:181], v[158:159], s[44:45] op_sel_hi:[1,1,0]
	v_exp_f32_e32 v170, v170
	v_exp_f32_e32 v171, v171
	v_pk_fma_f32 v[158:159], v[180:181], v[158:159], s[46:47] op_sel_hi:[1,1,0]
	v_max_f32_e32 v175, 0, v153
	v_pk_fma_f32 v[158:159], v[180:181], v[158:159], s[48:49] op_sel_hi:[1,1,0]
	v_pk_mul_f32 v[178:179], v[172:173], v[172:173]
	v_pk_mul_f32 v[158:159], v[180:181], v[158:159]
	v_pk_mul_f32 v[178:179], v[178:179], s[50:51] op_sel_hi:[1,0]
	v_pk_mul_f32 v[158:159], v[170:171], v[158:159]
	v_fma_f32 v176, |v172|, s38, 1.0
	v_fma_f32 v177, |v173|, s38, 1.0
	v_fma_f32 v158, -|v152|, v158, v174
	v_fma_f32 v159, -|v153|, v159, v175
	v_rcp_f32_e32 v176, v176
	v_rcp_f32_e32 v177, v177
	v_exp_f32_e32 v178, v178
	v_pk_fma_f32 v[174:175], v[176:177], s[40:41], v[146:147] op_sel_hi:[1,0,0]
	v_exp_f32_e32 v179, v179
	v_pk_fma_f32 v[174:175], v[176:177], v[174:175], s[44:45] op_sel_hi:[1,1,0]
	v_fma_f32 v180, |v156|, s38, 1.0
	v_fma_f32 v181, |v157|, s38, 1.0
	v_pk_fma_f32 v[174:175], v[176:177], v[174:175], s[46:47] op_sel_hi:[1,1,0]
	v_rcp_f32_e32 v180, v180
	v_rcp_f32_e32 v181, v181
	v_pk_fma_f32 v[174:175], v[176:177], v[174:175], s[48:49] op_sel_hi:[1,1,0]
	v_max_f32_e32 v170, 0, v172
	v_pk_mul_f32 v[174:175], v[176:177], v[174:175]
	v_pk_mul_f32 v[176:177], v[156:157], v[156:157]
	v_max_f32_e32 v171, 0, v173
	v_pk_mul_f32 v[174:175], v[178:179], v[174:175]
	v_max_f32_e32 v152, 0, v156
	v_fma_f32 v170, -|v172|, v174, v170
	v_fma_f32 v171, -|v173|, v175, v171
	v_pk_fma_f32 v[172:173], v[180:181], s[40:41], v[146:147] op_sel_hi:[1,0,0]
	v_pk_mul_f32 v[174:175], v[176:177], s[50:51] op_sel_hi:[1,0]
	v_pk_fma_f32 v[172:173], v[180:181], v[172:173], s[44:45] op_sel_hi:[1,1,0]
	v_exp_f32_e32 v174, v174
	v_exp_f32_e32 v175, v175
	v_pk_fma_f32 v[172:173], v[180:181], v[172:173], s[46:47] op_sel_hi:[1,1,0]
	v_max_f32_e32 v153, 0, v157
	v_pk_fma_f32 v[172:173], v[180:181], v[172:173], s[48:49] op_sel_hi:[1,1,0]
	v_add_co_u32_e32 v148, vcc, s85, v148
	v_pk_mul_f32 v[172:173], v[180:181], v[172:173]
	s_nop 0
	v_addc_co_u32_e32 v149, vcc, 0, v149, vcc
	v_pk_mul_f32 v[172:173], v[174:175], v[172:173]
	s_nop 0
	v_fma_f32 v156, -|v156|, v172, v152
	v_fma_f32 v157, -|v157|, v173, v153
	v_cvt_pk_bf16_f32 v152, v154, v155
	v_cvt_pk_bf16_f32 v153, v158, v159
	v_cvt_pk_bf16_f32 v154, v170, v171
	v_pk_add_f32 v[170:171], v[0:1], 0 op_sel_hi:[1,0]
	v_cvt_pk_bf16_f32 v155, v156, v157
	global_store_dwordx4 v[148:149], v[152:155], off
	v_pk_add_f32 v[148:149], v[6:7], 0 op_sel_hi:[1,0]
	s_nop 0
	v_pk_add_f32 v[152:153], v[4:5], 0 op_sel_hi:[1,0]
	v_and_b32_e32 v173, 0x7fffffff, v149
	v_fma_f32 v158, |v152|, s38, 1.0
	v_fma_f32 v159, |v153|, s38, 1.0
	v_pk_mul_f32 v[176:177], v[152:153], v[152:153]
	v_rcp_f32_e32 v158, v158
	v_rcp_f32_e32 v159, v159
	v_and_b32_e32 v172, 0x7fffffff, v148
	v_pk_mul_f32 v[176:177], v[176:177], s[50:51] op_sel_hi:[1,0]
	v_pk_fma_f32 v[178:179], v[172:173], s[38:39], 1.0 op_sel_hi:[1,0,0]
	v_pk_fma_f32 v[174:175], v[158:159], s[40:41], v[146:147] op_sel_hi:[1,0,0]
	v_exp_f32_e32 v176, v176
	v_pk_fma_f32 v[174:175], v[158:159], v[174:175], s[44:45] op_sel_hi:[1,1,0]
	v_exp_f32_e32 v177, v177
	v_pk_fma_f32 v[174:175], v[158:159], v[174:175], s[46:47] op_sel_hi:[1,1,0]
	v_rcp_f32_e32 v178, v178
	v_rcp_f32_e32 v179, v179
	v_pk_fma_f32 v[174:175], v[158:159], v[174:175], s[48:49] op_sel_hi:[1,1,0]
	v_max_f32_e32 v156, 0, v152
	v_pk_mul_f32 v[158:159], v[158:159], v[174:175]
	v_pk_mul_f32 v[174:175], v[148:149], v[148:149]
	v_max_f32_e32 v157, 0, v153
	v_pk_mul_f32 v[158:159], v[176:177], v[158:159]
	v_pk_add_f32 v[154:155], v[2:3], 0 op_sel_hi:[1,0]
	v_fma_f32 v152, -|v152|, v158, v156
	v_fma_f32 v153, -|v153|, v159, v157
	v_pk_fma_f32 v[156:157], v[178:179], s[40:41], v[146:147] op_sel_hi:[1,0,0]
	v_pk_mul_f32 v[158:159], v[174:175], s[50:51] op_sel_hi:[1,0]
	v_pk_fma_f32 v[156:157], v[178:179], v[156:157], s[44:45] op_sel_hi:[1,1,0]
	v_exp_f32_e32 v158, v158
	v_exp_f32_e32 v159, v159
	v_pk_fma_f32 v[156:157], v[178:179], v[156:157], s[46:47] op_sel_hi:[1,1,0]
	v_max_f32_e32 v148, 0, v148
	v_pk_fma_f32 v[156:157], v[178:179], v[156:157], s[48:49] op_sel_hi:[1,1,0]
	v_max_f32_e32 v149, 0, v149
	v_pk_mul_f32 v[156:157], v[178:179], v[156:157]
	v_pk_mul_f32 v[176:177], v[170:171], v[170:171]
	v_pk_mul_f32 v[156:157], v[158:159], v[156:157]
	v_fma_f32 v174, |v170|, s38, 1.0
	v_fma_f32 v175, |v171|, s38, 1.0
	v_pk_fma_f32 v[148:149], v[172:173], v[156:157], v[148:149] neg_lo:[1,0,0] neg_hi:[1,0,0]
	v_rcp_f32_e32 v174, v174
	v_rcp_f32_e32 v175, v175
	v_pk_mul_f32 v[176:177], v[176:177], s[50:51] op_sel_hi:[1,0]
	v_pk_fma_f32 v[172:173], v[174:175], s[40:41], v[146:147] op_sel_hi:[1,0,0]
	v_exp_f32_e32 v176, v176
	v_pk_fma_f32 v[172:173], v[174:175], v[172:173], s[44:45] op_sel_hi:[1,1,0]
	v_exp_f32_e32 v177, v177
	v_fma_f32 v178, |v154|, s38, 1.0
	v_fma_f32 v179, |v155|, s38, 1.0
	v_pk_fma_f32 v[172:173], v[174:175], v[172:173], s[46:47] op_sel_hi:[1,1,0]
	v_rcp_f32_e32 v178, v178
	v_rcp_f32_e32 v179, v179
	v_pk_fma_f32 v[172:173], v[174:175], v[172:173], s[48:49] op_sel_hi:[1,1,0]
	v_max_f32_e32 v158, 0, v170
	v_pk_mul_f32 v[172:173], v[174:175], v[172:173]
	v_pk_mul_f32 v[174:175], v[154:155], v[154:155]
	v_max_f32_e32 v159, 0, v171
	v_pk_mul_f32 v[172:173], v[176:177], v[172:173]
	v_pk_fma_f32 v[146:147], v[178:179], s[40:41], v[146:147] op_sel_hi:[1,0,0]
	v_fma_f32 v158, -|v170|, v172, v158
	v_fma_f32 v159, -|v171|, v173, v159
	v_pk_mul_f32 v[170:171], v[174:175], s[50:51] op_sel_hi:[1,0]
	v_pk_fma_f32 v[146:147], v[178:179], v[146:147], s[44:45] op_sel_hi:[1,1,0]
	v_exp_f32_e32 v170, v170
	v_exp_f32_e32 v171, v171
	v_pk_fma_f32 v[146:147], v[178:179], v[146:147], s[46:47] op_sel_hi:[1,1,0]
	v_max_f32_e32 v156, 0, v154
	v_pk_fma_f32 v[146:147], v[178:179], v[146:147], s[48:49] op_sel_hi:[1,1,0]
	v_max_f32_e32 v157, 0, v155
	v_pk_mul_f32 v[146:147], v[178:179], v[146:147]
	s_nop 0
	v_pk_mul_f32 v[146:147], v[170:171], v[146:147]
	s_nop 0
	v_fma_f32 v154, -|v154|, v146, v156
	v_fma_f32 v155, -|v155|, v147, v157
	v_cvt_pk_bf16_f32 v146, v152, v153
	v_cvt_pk_bf16_f32 v147, v148, v149
	v_cvt_pk_bf16_f32 v148, v158, v159
	s_nop 0
	v_cvt_pk_bf16_f32 v149, v154, v155
	global_store_dwordx4 v[150:151], v[146:149], off offset:256

.LBB0_546:
	v_lshl_add_u32 v194, s40, 8, v213
	v_ashrrev_i32_e32 v195, 31, v194
	s_nop 7
	v_lshl_add_u64 v[196:197], v[194:195], 3, s[14:15]
	global_load_dwordx2 v[128:129], v[196:197], off
	v_lshl_or_b32 v192, s8, 8, v215
	v_ashrrev_i32_e32 v193, 31, v192
	v_lshl_add_u64 v[198:199], v[192:193], 2, s[10:11]
	v_lshlrev_b64 v[130:131], 13, v[194:195]
	v_lshl_add_u64 v[130:131], v[198:199], 0, v[130:131]
	global_load_dwordx4 v[224:227], v[130:131], off offset:16 nt
	global_load_dwordx4 v[228:231], v[130:131], off nt
	global_load_dwordx4 v[232:235], v[130:131], off offset:528 nt
	global_load_dwordx4 v[236:239], v[130:131], off offset:512 nt
	v_or_b32_e32 v206, 16, v194
	v_or_b32_e32 v202, 32, v194
	v_or_b32_e32 v200, 48, v194
	v_and_b32_e32 v132, 64, v221
	v_ashrrev_i32_e32 v207, 31, v206
	v_ashrrev_i32_e32 v203, 31, v202
	v_ashrrev_i32_e32 v201, 31, v200
	v_add_u32_e32 v244, 64, v132
	v_lshl_add_u64 v[130:131], v[206:207], 3, s[14:15]
	v_lshlrev_b64 v[132:133], 13, v[206:207]
	v_lshl_add_u64 v[134:135], v[202:203], 3, s[14:15]
	v_lshl_add_u64 v[138:139], v[200:201], 3, s[14:15]
	v_lshlrev_b64 v[136:137], 13, v[202:203]
	v_lshlrev_b64 v[140:141], 13, v[200:201]
	global_load_dwordx2 v[210:211], v[130:131], off
	global_load_dwordx2 v[208:209], v[134:135], off
	global_load_dwordx2 v[204:205], v[138:139], off
	v_lshl_add_u64 v[130:131], v[198:199], 0, v[132:133]
	v_lshl_add_u64 v[132:133], v[198:199], 0, v[136:137]
	v_lshl_add_u64 v[134:135], v[198:199], 0, v[140:141]
	global_load_dwordx4 v[168:171], v[130:131], off offset:16 nt
	global_load_dwordx4 v[172:175], v[130:131], off nt
	global_load_dwordx4 v[160:163], v[130:131], off offset:528 nt
	global_load_dwordx4 v[164:167], v[130:131], off offset:512 nt
	global_load_dwordx4 v[152:155], v[132:133], off offset:16 nt
	global_load_dwordx4 v[156:159], v[132:133], off nt
	global_load_dwordx4 v[144:147], v[132:133], off offset:528 nt
	global_load_dwordx4 v[148:151], v[132:133], off offset:512 nt
	global_load_dwordx4 v[136:139], v[134:135], off offset:16 nt
	global_load_dwordx4 v[140:143], v[134:135], off nt
	v_xor_b32_e32 v212, 16, v221
	v_cmp_lt_i32_e64 s[8:9], v212, v244
	v_lshlrev_b64 v[222:223], 12, v[194:195]
	v_xor_b32_e32 v243, 32, v221
	v_cndmask_b32_e64 v212, v221, v212, s[8:9]
	s_waitcnt vmcnt(0)
	v_ffbh_u32_e32 v130, v129
	v_min_u32_e32 v240, 32, v130
	v_lshlrev_b64 v[128:129], v240, v[128:129]
	v_min_u32_e32 v128, 1, v128
	v_or_b32_e32 v128, v129, v128
	v_cvt_f32_u32_e32 v241, v128
	global_load_dwordx4 v[128:131], v[134:135], off offset:528 nt
	s_nop 0
	global_load_dwordx4 v[132:135], v[134:135], off offset:512 nt
	v_sub_u32_e32 v240, 32, v240
	v_ldexp_f32 v240, v241, v240
	v_mul_f32_e32 v240, 0x2f800000, v240
	v_fmamk_f32 v240, v240, 0x3a800000, v219
	v_mul_f32_e32 v241, 0x4f800000, v240
	v_cmp_gt_f32_e32 vcc, s57, v240
	s_nop 1
	v_cndmask_b32_e32 v242, v240, v241, vcc
	v_sqrt_f32_e32 v245, v242
	v_lshl_add_u64 v[240:241], s[18:19], 0, v[222:223]
	v_lshlrev_b32_e32 v222, 2, v212
	v_lshl_add_u64 v[240:241], v[192:193], 1, v[240:241]
	v_add_u32_e32 v212, -1, v245
	v_add_u32_e32 v223, 1, v245
	v_fma_f32 v246, -v212, v245, v242
	v_fma_f32 v247, -v223, v245, v242
	v_cmp_ge_f32_e64 s[8:9], 0, v246
	s_nop 1
	v_cndmask_b32_e64 v212, v245, v212, s[8:9]
	v_cmp_lt_f32_e64 s[8:9], 0, v247
	s_nop 1
	v_cndmask_b32_e64 v212, v212, v223, s[8:9]
	v_mul_f32_e32 v223, 0x37800000, v212
	v_cndmask_b32_e32 v212, v212, v223, vcc
	v_cmp_class_f32_e32 vcc, v242, v220
	s_nop 1
	v_cndmask_b32_e32 v212, v212, v242, vcc
	v_div_scale_f32 v223, s[0:1], v212, v212, 1.0
	v_rcp_f32_e32 v242, v223
	v_div_scale_f32 v245, vcc, 1.0, v212, 1.0
	v_fma_f32 v246, -v223, v242, 1.0
	v_fmac_f32_e32 v242, v246, v242
	v_mul_f32_e32 v246, v245, v242
	v_fma_f32 v247, -v223, v246, v245
	v_fmac_f32_e32 v246, v247, v242
	v_fma_f32 v223, -v223, v246, v245
	v_div_fmas_f32 v223, v223, v242, v246
	v_div_fixup_f32 v242, v223, v212, 1.0
	v_pk_fma_f32 v[126:127], v[126:127], v[242:243], v[230:231] op_sel_hi:[1,0,1]
	v_pk_fma_f32 v[124:125], v[124:125], v[242:243], v[228:229] op_sel_hi:[1,0,1]
	v_pk_fma_f32 v[118:119], v[118:119], v[242:243], v[238:239] op_sel_hi:[1,0,1]
	v_pk_fma_f32 v[116:117], v[116:117], v[242:243], v[236:237] op_sel_hi:[1,0,1]
	v_pk_fma_f32 v[122:123], v[122:123], v[242:243], v[226:227] op_sel_hi:[1,0,1]
	v_pk_fma_f32 v[120:121], v[120:121], v[242:243], v[224:225] op_sel_hi:[1,0,1]
	v_pk_fma_f32 v[224:225], v[114:115], v[242:243], v[234:235] op_sel_hi:[1,0,1]
	v_pk_fma_f32 v[226:227], v[112:113], v[242:243], v[232:233] op_sel_hi:[1,0,1]
	v_mul_f32_e32 v114, v125, v125
	v_mul_f32_e32 v115, v127, v127
	v_cvt_pk_bf16_f32 v112, v124, v125
	v_cvt_pk_bf16_f32 v113, v126, v127
	v_mul_f32_e32 v125, v117, v117
	v_mul_f32_e32 v127, v119, v119
	v_mul_f32_e32 v212, v121, v121
	v_mul_f32_e32 v228, v227, v227
	v_fmac_f32_e32 v114, v124, v124
	v_fmac_f32_e32 v115, v126, v126
	v_fmac_f32_e32 v125, v116, v116
	v_fmac_f32_e32 v127, v118, v118
	v_mul_f32_e32 v223, v123, v123
	v_mul_f32_e32 v229, v225, v225
	v_fmac_f32_e32 v212, v120, v120
	v_fmac_f32_e32 v228, v226, v226
	v_add_f32_e32 v114, v114, v115
	v_add_f32_e32 v115, v125, v127
	v_fmac_f32_e32 v223, v122, v122
	v_fmac_f32_e32 v229, v224, v224
	v_add_f32_e32 v114, v212, v114
	v_add_f32_e32 v115, v228, v115
	v_add_f32_e32 v114, v223, v114
	v_add_f32_e32 v115, v229, v115
	v_add_f32_e32 v124, v114, v115
	ds_bpermute_b32 v125, v222, v124
	v_cmp_lt_i32_e32 vcc, v243, v244
	v_cvt_pk_bf16_f32 v114, v120, v121
	v_cvt_pk_bf16_f32 v115, v122, v123
	global_store_dwordx4 v[240:241], v[112:115], off
	s_nop 1
	v_cndmask_b32_e32 v113, v221, v243, vcc
	s_waitcnt lgkmcnt(0)
	v_add_f32_e32 v112, v124, v125
	v_lshlrev_b32_e32 v126, 2, v113
	ds_bpermute_b32 v113, v126, v112
	v_cvt_pk_bf16_f32 v114, v116, v117
	v_cvt_pk_bf16_f32 v115, v118, v119
	v_cvt_pk_bf16_f32 v116, v226, v227
	v_cvt_pk_bf16_f32 v117, v224, v225
	global_store_dwordx4 v[240:241], v[114:117], off offset:256
	s_and_saveexec_b64 s[8:9], s[4:5]
	s_cbranch_execz .LBB0_548
	s_waitcnt lgkmcnt(0)
	v_add_f32_e32 v112, v112, v113
	v_mul_f32_e32 v112, 0x4f800000, v112
	v_trunc_f32_e32 v112, v112
	v_mul_f32_e32 v113, 0x2f800000, v112
	v_floor_f32_e32 v113, v113
	v_fmac_f32_e32 v112, 0xcf800000, v113
	v_cvt_u32_f32_e32 v112, v112
	v_cvt_u32_f32_e32 v113, v113
	v_lshl_add_u64 v[114:115], v[194:195], 3, s[16:17]
	global_atomic_add_x2 v[114:115], v[112:113], off

.LBB0_639:
	v_mov_b32_e32 v201, v192
	v_mov_b32_e32 v149, v193
	s_nop 7
	s_movk_i32 s1, 0x100
	v_lshl_add_u32 v134, v149, 4, v201
	v_add_u32_e32 v135, s84, v134
	v_cmp_gt_i32_e32 vcc, s1, v135
	s_and_saveexec_b64 s[6:7], vcc
	s_cbranch_execz .LBB0_641
	v_lshlrev_b32_e32 v135, 3, v135
	v_lshlrev_b32_e32 v134, 3, v134
	v_and_b32_e32 v135, 0xfffffe00, v135
	v_and_b32_e32 v134, 0x1f8, v134
	v_add3_u32 v134, s96, v135, v134
	ds_write_b64 v134, v[132:133]

.LBB0_879:
	s_or_b32 s1, s0, s47
	v_mov_b32_e32 v195, v186
	v_mov_b32_e32 v196, v185
	s_nop 7
	s_lshl_b32 s0, s1, 8
	v_add_u32_e32 v194, s55, v196
	v_lshl_add_u32 v174, v195, 3, s69
	v_add_u32_e32 v172, s0, v194
	v_ashrrev_i32_e32 v175, 31, v174
	v_ashrrev_i32_e32 v173, 31, v172
	v_lshl_add_u64 v[182:183], v[174:175], 1, s[10:11]
	v_lshlrev_b64 v[242:243], 2, v[174:175]
	v_lshl_add_u64 v[242:243], s[12:13], 0, v[242:243]
	v_lshlrev_b64 v[128:129], 12, v[172:173]
	v_lshl_add_u64 v[176:177], v[182:183], 0, v[128:129]
	global_load_dwordx4 v[178:181], v[176:177], off
	global_load_dwordx4 v[198:201], v[176:177], off offset:256
	v_add_u32_e32 v170, 16, v172
	v_add_u32_e32 v168, 32, v172
	v_add_u32_e32 v166, 48, v172
	v_ashrrev_i32_e32 v171, 31, v170
	v_ashrrev_i32_e32 v169, 31, v168
	v_ashrrev_i32_e32 v167, 31, v166
	v_lshlrev_b64 v[128:129], 12, v[170:171]
	v_lshlrev_b64 v[130:131], 12, v[168:169]
	v_lshlrev_b64 v[132:133], 12, v[166:167]
	v_lshl_add_u64 v[128:129], v[182:183], 0, v[128:129]
	v_lshl_add_u64 v[130:131], v[182:183], 0, v[130:131]
	v_lshl_add_u64 v[202:203], v[182:183], 0, v[132:133]
	global_load_dwordx4 v[148:151], v[128:129], off
	global_load_dwordx4 v[144:147], v[128:129], off offset:256
	global_load_dwordx4 v[140:143], v[130:131], off
	global_load_dwordx4 v[136:139], v[130:131], off offset:256
	global_load_dwordx4 v[132:135], v[202:203], off
	s_nop 0
	global_load_dwordx4 v[128:131], v[202:203], off offset:256
	v_add_co_u32_e32 v224, vcc, 0x80000, v176
	s_nop 1
	v_addc_co_u32_e32 v225, vcc, 0, v177, vcc
	global_load_dwordx4 v[216:219], v[224:225], off
	global_load_dwordx4 v[220:223], v[224:225], off offset:256
	v_add_co_u32_e32 v252, vcc, 0x90000, v176
	s_nop 1
	v_addc_co_u32_e32 v253, vcc, 0, v177, vcc
	global_load_dwordx4 v[244:247], v[252:253], off
	global_load_dwordx4 v[248:251], v[252:253], off offset:256
	v_add_co_u32_e32 v224, vcc, 0xa0000, v176
	s_nop 1
	v_addc_co_u32_e32 v225, vcc, 0, v177, vcc
	global_load_dwordx4 v[226:229], v[224:225], off
	global_load_dwordx4 v[230:233], v[224:225], off offset:256
	v_add_co_u32_e32 v252, vcc, 0xb0000, v176
	s_nop 1
	v_addc_co_u32_e32 v253, vcc, 0, v177, vcc
	global_load_dwordx4 v[234:237], v[252:253], off
	global_load_dwordx4 v[238:241], v[252:253], off offset:256
	v_and_b32_e32 v202, 64, v191
	v_add_u32_e32 v210, 64, v202
	v_xor_b32_e32 v197, 16, v191
	v_cmp_lt_i32_e32 vcc, v197, v210
	v_cmp_eq_u32_e64 s[4:5], 0, v195
	s_waitcnt vmcnt(8)
	v_lshlrev_b32_e32 v202, 16, v178
	v_and_b32_e32 v203, 0xffff0000, v178
	v_lshlrev_b32_e32 v178, 16, v179
	v_and_b32_e32 v179, 0xffff0000, v179
	v_lshlrev_b32_e32 v206, 16, v198
	v_and_b32_e32 v207, 0xffff0000, v198
	v_lshlrev_b32_e32 v198, 16, v199
	v_and_b32_e32 v199, 0xffff0000, v199
	v_lshlrev_b32_e32 v204, 16, v180
	v_and_b32_e32 v205, 0xffff0000, v180
	v_lshlrev_b32_e32 v208, 16, v200
	v_and_b32_e32 v209, 0xffff0000, v200
	v_pk_add_f32 v[126:127], v[126:127], v[178:179]
	v_pk_add_f32 v[124:125], v[124:125], v[202:203]
	v_pk_add_f32 v[118:119], v[118:119], v[198:199]
	v_pk_add_f32 v[116:117], v[116:117], v[206:207]
	v_lshlrev_b32_e32 v180, 16, v181
	v_and_b32_e32 v181, 0xffff0000, v181
	v_lshlrev_b32_e32 v200, 16, v201
	v_and_b32_e32 v201, 0xffff0000, v201
	v_pk_add_f32 v[120:121], v[120:121], v[204:205]
	v_pk_add_f32 v[112:113], v[112:113], v[208:209]
	v_mul_f32_e32 v178, v125, v125
	v_mul_f32_e32 v179, v127, v127
	v_mul_f32_e32 v198, v117, v117
	v_mul_f32_e32 v199, v119, v119
	v_pk_add_f32 v[122:123], v[122:123], v[180:181]
	v_pk_add_f32 v[114:115], v[114:115], v[200:201]
	v_mul_f32_e32 v180, v121, v121
	v_mul_f32_e32 v200, v113, v113
	v_fmac_f32_e32 v178, v124, v124
	v_fmac_f32_e32 v179, v126, v126
	v_fmac_f32_e32 v198, v116, v116
	v_fmac_f32_e32 v199, v118, v118
	v_mul_f32_e32 v181, v123, v123
	v_mul_f32_e32 v201, v115, v115
	v_fmac_f32_e32 v180, v120, v120
	v_fmac_f32_e32 v200, v112, v112
	v_add_f32_e32 v178, v178, v179
	v_add_f32_e32 v179, v198, v199
	v_fmac_f32_e32 v181, v122, v122
	v_fmac_f32_e32 v201, v114, v114
	v_add_f32_e32 v178, v180, v178
	v_add_f32_e32 v179, v200, v179
	v_cndmask_b32_e32 v197, v191, v197, vcc
	v_add_f32_e32 v178, v181, v178
	v_add_f32_e32 v179, v201, v179
	v_lshlrev_b32_e32 v197, 2, v197
	v_add_f32_e32 v178, v178, v179
	ds_bpermute_b32 v179, v197, v178
	v_xor_b32_e32 v180, 32, v191
	v_cmp_lt_i32_e32 vcc, v180, v210
	s_waitcnt lgkmcnt(0)
	v_add_f32_e32 v178, v178, v179
	v_cndmask_b32_e32 v180, v191, v180, vcc
	v_lshlrev_b32_e32 v198, 2, v180
	ds_bpermute_b32 v179, v198, v178
	s_and_saveexec_b64 s[38:39], s[4:5]
	s_cbranch_execz .LBB0_881
	s_waitcnt lgkmcnt(0)
	v_add_f32_e32 v178, v178, v179
	v_lshl_add_u32 v179, v194, 4, s60
	ds_write_b32 v179, v178
